# ODIN epilogue stores as global_store (strict in-order vmcnt with the counted waits); peeled-iteration waits of the ODIN instance counted past all 16 tile stores (vmcnt 32)
# baseline (speedup 1.0000x reference)
; #define PG8_STAGE(bufoff, gbase, voff) do { _Pragma("unroll") for (int _i = 0; _i < 2; ++_i) \
;         __builtin_amdgcn_global_load_lds((const unsigned*)((const char*)(gbase) + (voff)[_i]), (LAS unsigned*)(lds + (bufoff) + ldsw + _i * 8192), 16, 0, 0); } while (0)
; #define PG8_LDA(dst, b, h) do { _Pragma("unroll") for (int m = 0; m < 4; ++m) _Pragma("unroll") for (int k = 0; k < 2; ++k) dst[m][k] = *(const LAS bf16x8*)(lds + PG8_SA(b, h) + aoff + m * 2048 + k * 1024); } while (0)
; #define PG8_LDB(dst, b, h) do { _Pragma("unroll") for (int n = 0; n < 2; ++n) _Pragma("unroll") for (int k = 0; k < 2; ++k) dst[n][k] = *(const LAS bf16x8*)(lds + PG8_SB(b, h) + boff + n * 2048 + k * 1024); } while (0)
; #define PG8_MMA(ai, bj, At, Bt) do { __builtin_amdgcn_s_setprio(1); _Pragma("unroll") for (int m = 0; m < 4; ++m) _Pragma("unroll") for (int n = 0; n < 2; ++n) _Pragma("unroll") for (int k = 0; k < 2; ++k) \
;         acc[ai][bj][m][n] = __builtin_amdgcn_mfma_f32_16x16x32_bf16(Bt[n][k], At[m][k], acc[ai][bj][m][n], 0, 0, 0); __builtin_amdgcn_s_setprio(0); } while (0)
; #define PG8_WAIT_V(n) asm volatile("s_waitcnt vmcnt(" #n ")" ::: "memory")
; #define PG8_WAIT_L(n) asm volatile("s_waitcnt lgkmcnt(" #n ")" ::: "memory")
; #define PG8_BAR __builtin_amdgcn_s_barrier()
; #define PG8_SCHED __builtin_amdgcn_sched_barrier(0)
; template <int MODE> __device__ __forceinline__ void gemm_phase(LAS unsigned char* lds, const GD& g, const int tid) {
;     ...
;             PG8_LDB(B0, 0, 0); PG8_LDB(B1, 0, 1); PG8_SCHED; PG8_LDA(At, 0, 0); PG8_STAGE(PG8_SA(1, 1), a1 + hsA, voffA);
;             PG8_WAIT_V(8); PG8_WAIT_L(0); PG8_BAR; PG8_MMA(0, 0, At, B0); PG8_MMA(0, 1, At, B1); PG8_BAR; PG8_SCHED;
;             PG8_LDA(At, 0, 1); PG8_STAGE(PG8_SB(0, 0), b2, voffB); PG8_STAGE(PG8_SB(0, 1), b2 + hsB, voffB); PG8_STAGE(PG8_SA(0, 0), a2, voffA);
;             PG8_WAIT_V(8); PG8_WAIT_L(0); PG8_BAR; PG8_MMA(1, 0, At, B0); PG8_MMA(1, 1, At, B1); PG8_BAR; PG8_SCHED;
.Lpeel329_329:
	s_add_i32 s1, s1, 2
	s_add_u32 vcc_lo, s68, s20
	s_addc_u32 vcc_hi, s69, s21
	s_add_i32 s11, 0, 0x10000
	v_add_u32_e32 v1, s11, v173
	s_add_i32 s14, 0, 0x14000
	ds_read_b128 v[146:149], v1
	ds_read_b128 v[150:153], v1 offset:1024
	ds_read_b128 v[154:157], v1 offset:2048
	ds_read_b128 v[158:161], v1 offset:3072
	v_add_u32_e32 v1, s14, v173
	ds_read_b128 v[184:187], v1
	ds_read_b128 v[188:191], v1 offset:1024
	ds_read_b128 v[196:199], v1 offset:2048
	ds_read_b128 v[204:207], v1 offset:3072
	v_lshl_add_u64 v[192:193], s[6:7], 0, v[144:145]
	s_add_i32 m0, s26, 0xc000
	ds_read_b128 v[220:223], v182
	ds_read_b128 v[224:227], v182 offset:1024
	ds_read_b128 v[228:231], v182 offset:2048
	ds_read_b128 v[232:235], v182 offset:3072
	ds_read_b128 v[236:239], v182 offset:4096
	ds_read_b128 v[240:243], v182 offset:5120
	ds_read_b128 v[244:247], v182 offset:6144
	ds_read_b128 v[248:251], v182 offset:7168
	global_load_lds_dwordx4 v[192:193], off
	v_lshl_add_u64 v[192:193], s[6:7], 0, v[142:143]
	s_add_i32 m0, s26, 0xe000
	s_nop 0
	global_load_lds_dwordx4 v[192:193], off
	s_waitcnt vmcnt(32)
	s_waitcnt lgkmcnt(0)
	s_barrier
	s_setprio 1
	s_waitcnt lgkmcnt(0)
	v_mfma_f32_16x16x32_bf16 v[126:129], v[146:149], v[220:223], v[126:129]
	v_mfma_f32_16x16x32_bf16 v[122:125], v[154:157], v[220:223], v[122:125]
	v_mfma_f32_16x16x32_bf16 v[118:121], v[146:149], v[228:231], v[118:121]
	v_mfma_f32_16x16x32_bf16 v[110:113], v[154:157], v[228:231], v[110:113]
	v_mfma_f32_16x16x32_bf16 v[102:105], v[146:149], v[236:239], v[102:105]
	v_mfma_f32_16x16x32_bf16 v[94:97], v[154:157], v[236:239], v[94:97]
	v_mfma_f32_16x16x32_bf16 v[86:89], v[146:149], v[244:247], v[86:89]
	v_mfma_f32_16x16x32_bf16 v[78:81], v[154:157], v[244:247], v[78:81]
	v_mfma_f32_16x16x32_bf16 v[126:129], v[150:153], v[224:227], v[126:129]
	v_mfma_f32_16x16x32_bf16 v[122:125], v[158:161], v[224:227], v[122:125]
	v_mfma_f32_16x16x32_bf16 v[118:121], v[150:153], v[232:235], v[118:121]
	v_mfma_f32_16x16x32_bf16 v[110:113], v[158:161], v[232:235], v[110:113]
	v_mfma_f32_16x16x32_bf16 v[102:105], v[150:153], v[240:243], v[102:105]
	v_mfma_f32_16x16x32_bf16 v[94:97], v[158:161], v[240:243], v[94:97]
	v_mfma_f32_16x16x32_bf16 v[86:89], v[150:153], v[248:251], v[86:89]
	v_mfma_f32_16x16x32_bf16 v[78:81], v[158:161], v[248:251], v[78:81]
	s_setprio 0
	s_setprio 1
	v_mfma_f32_16x16x32_bf16 v[114:117], v[184:187], v[220:223], v[114:117]
	v_mfma_f32_16x16x32_bf16 v[106:109], v[196:199], v[220:223], v[106:109]
	v_mfma_f32_16x16x32_bf16 v[98:101], v[184:187], v[228:231], v[98:101]
	v_mfma_f32_16x16x32_bf16 v[90:93], v[196:199], v[228:231], v[90:93]
	v_mfma_f32_16x16x32_bf16 v[82:85], v[184:187], v[236:239], v[82:85]
	v_mfma_f32_16x16x32_bf16 v[74:77], v[196:199], v[236:239], v[74:77]
	v_mfma_f32_16x16x32_bf16 v[70:73], v[184:187], v[244:247], v[70:73]
	v_mfma_f32_16x16x32_bf16 v[66:69], v[196:199], v[244:247], v[66:69]
	v_mfma_f32_16x16x32_bf16 v[114:117], v[188:191], v[224:227], v[114:117]
	v_mfma_f32_16x16x32_bf16 v[106:109], v[204:207], v[224:227], v[106:109]
	v_mfma_f32_16x16x32_bf16 v[98:101], v[188:191], v[232:235], v[98:101]
	v_mfma_f32_16x16x32_bf16 v[90:93], v[204:207], v[232:235], v[90:93]
	v_mfma_f32_16x16x32_bf16 v[82:85], v[188:191], v[240:243], v[82:85]
	v_mfma_f32_16x16x32_bf16 v[74:77], v[204:207], v[240:243], v[74:77]
	v_mfma_f32_16x16x32_bf16 v[70:73], v[188:191], v[248:251], v[70:73]
	v_mfma_f32_16x16x32_bf16 v[66:69], v[204:207], v[248:251], v[66:69]
	s_setprio 0
	s_barrier
	s_add_i32 s11, s11, s25
	v_lshl_add_u64 v[192:193], s[64:65], 0, v[132:133]
	s_mov_b32 m0, s11
	ds_read_b128 v[220:223], v182 offset:16384
	ds_read_b128 v[224:227], v182 offset:17408
	ds_read_b128 v[228:231], v182 offset:18432
	ds_read_b128 v[232:235], v182 offset:19456
	ds_read_b128 v[236:239], v182 offset:20480
	ds_read_b128 v[240:243], v182 offset:21504
	ds_read_b128 v[244:247], v182 offset:22528
	ds_read_b128 v[248:251], v182 offset:23552
	global_load_lds_dwordx4 v[192:193], off
	s_add_i32 m0, s11, 0x2000
	s_add_u32 s12, s64, s58
	v_lshl_add_u64 v[192:193], s[64:65], 0, v[136:137]
	s_addc_u32 s13, s65, s59
	s_add_i32 s11, s14, s25
	global_load_lds_dwordx4 v[192:193], off
	v_lshl_add_u64 v[192:193], s[12:13], 0, v[132:133]
	s_mov_b32 m0, s11
	s_nop 0
	global_load_lds_dwordx4 v[192:193], off
	v_lshl_add_u64 v[192:193], s[12:13], 0, v[136:137]
	s_add_i32 m0, s11, 0x2000
	s_nop 0
	global_load_lds_dwordx4 v[192:193], off
	v_lshl_add_u64 v[192:193], s[68:69], 0, v[130:131]
	s_mov_b32 m0, s26
	s_nop 0
	global_load_lds_dwordx4 v[192:193], off
	v_lshl_add_u64 v[192:193], s[68:69], 0, v[134:135]
	s_mov_b32 m0, s27
	s_nop 0
	global_load_lds_dwordx4 v[192:193], off
	s_waitcnt vmcnt(32)
	s_waitcnt lgkmcnt(0)
	s_barrier
; #define PG8_STAGE(bufoff, gbase, voff) do { _Pragma("unroll") for (int _i = 0; _i < 2; ++_i) \
;         __builtin_amdgcn_global_load_lds((const unsigned*)((const char*)(gbase) + (voff)[_i]), (LAS unsigned*)(lds + (bufoff) + ldsw + _i * 8192), 16, 0, 0); } while (0)
; #define PG8_LDA(dst, b, h) do { _Pragma("unroll") for (int m = 0; m < 4; ++m) _Pragma("unroll") for (int k = 0; k < 2; ++k) dst[m][k] = *(const LAS bf16x8*)(lds + PG8_SA(b, h) + aoff + m * 2048 + k * 1024); } while (0)
; #define PG8_LDB(dst, b, h) do { _Pragma("unroll") for (int n = 0; n < 2; ++n) _Pragma("unroll") for (int k = 0; k < 2; ++k) dst[n][k] = *(const LAS bf16x8*)(lds + PG8_SB(b, h) + boff + n * 2048 + k * 1024); } while (0)
; #define PG8_MMA(ai, bj, At, Bt) do { __builtin_amdgcn_s_setprio(1); _Pragma("unroll") for (int m = 0; m < 4; ++m) _Pragma("unroll") for (int n = 0; n < 2; ++n) _Pragma("unroll") for (int k = 0; k < 2; ++k) \
;         acc[ai][bj][m][n] = __builtin_amdgcn_mfma_f32_16x16x32_bf16(Bt[n][k], At[m][k], acc[ai][bj][m][n], 0, 0, 0); __builtin_amdgcn_s_setprio(0); } while (0)
; #define PG8_WAIT_V(n) asm volatile("s_waitcnt vmcnt(" #n ")" ::: "memory")
; #define PG8_WAIT_L(n) asm volatile("s_waitcnt lgkmcnt(" #n ")" ::: "memory")
; #define PG8_BAR __builtin_amdgcn_s_barrier()
; #define PG8_SCHED __builtin_amdgcn_sched_barrier(0)
; template <int MODE> __device__ __forceinline__ void gemm_phase(LAS unsigned char* lds, const GD& g, const int tid) {
;     ...
;             PG8_WAIT_V(8); PG8_WAIT_L(0); PG8_BAR; PG8_MMA(1, 0, At, B0); PG8_MMA(1, 1, At, B1); PG8_BAR; PG8_SCHED;
;             PG8_LDB(B0, 1, 0); PG8_LDB(B1, 1, 1); PG8_SCHED; PG8_LDA(At, 1, 0); PG8_STAGE(PG8_SA(0, 1), a2 + hsA, voffA);
;             PG8_WAIT_V(8); PG8_WAIT_L(0); PG8_BAR; PG8_MMA(0, 0, At, B0); PG8_MMA(0, 1, At, B1); PG8_BAR; PG8_SCHED;
	s_setprio 1
	s_waitcnt lgkmcnt(0)
	v_mfma_f32_16x16x32_bf16 v[62:65], v[146:149], v[220:223], v[62:65]
	v_mfma_f32_16x16x32_bf16 v[58:61], v[154:157], v[220:223], v[58:61]
	v_mfma_f32_16x16x32_bf16 v[54:57], v[146:149], v[228:231], v[54:57]
	v_mfma_f32_16x16x32_bf16 v[46:49], v[154:157], v[228:231], v[46:49]
	v_mfma_f32_16x16x32_bf16 v[38:41], v[146:149], v[236:239], v[38:41]
	v_mfma_f32_16x16x32_bf16 v[30:33], v[154:157], v[236:239], v[30:33]
	v_mfma_f32_16x16x32_bf16 v[22:25], v[146:149], v[244:247], v[22:25]
	v_mfma_f32_16x16x32_bf16 v[14:17], v[154:157], v[244:247], v[14:17]
	v_mfma_f32_16x16x32_bf16 v[62:65], v[150:153], v[224:227], v[62:65]
	v_mfma_f32_16x16x32_bf16 v[58:61], v[158:161], v[224:227], v[58:61]
	v_mfma_f32_16x16x32_bf16 v[54:57], v[150:153], v[232:235], v[54:57]
	v_mfma_f32_16x16x32_bf16 v[46:49], v[158:161], v[232:235], v[46:49]
	v_mfma_f32_16x16x32_bf16 v[38:41], v[150:153], v[240:243], v[38:41]
	v_mfma_f32_16x16x32_bf16 v[30:33], v[158:161], v[240:243], v[30:33]
	v_mfma_f32_16x16x32_bf16 v[22:25], v[150:153], v[248:251], v[22:25]
	v_mfma_f32_16x16x32_bf16 v[14:17], v[158:161], v[248:251], v[14:17]
	s_setprio 0
	s_setprio 1
	v_mfma_f32_16x16x32_bf16 v[50:53], v[184:187], v[220:223], v[50:53]
	v_mfma_f32_16x16x32_bf16 v[42:45], v[196:199], v[220:223], v[42:45]
	v_mfma_f32_16x16x32_bf16 v[34:37], v[184:187], v[228:231], v[34:37]
	v_mfma_f32_16x16x32_bf16 v[26:29], v[196:199], v[228:231], v[26:29]
	v_mfma_f32_16x16x32_bf16 v[18:21], v[184:187], v[236:239], v[18:21]
	v_mfma_f32_16x16x32_bf16 v[10:13], v[196:199], v[236:239], v[10:13]
	v_mfma_f32_16x16x32_bf16 v[6:9], v[184:187], v[244:247], v[6:9]
	v_mfma_f32_16x16x32_bf16 v[2:5], v[196:199], v[244:247], v[2:5]
	v_mfma_f32_16x16x32_bf16 v[50:53], v[188:191], v[224:227], v[50:53]
	v_mfma_f32_16x16x32_bf16 v[42:45], v[204:207], v[224:227], v[42:45]
	v_mfma_f32_16x16x32_bf16 v[34:37], v[188:191], v[232:235], v[34:37]
	v_mfma_f32_16x16x32_bf16 v[26:29], v[204:207], v[232:235], v[26:29]
	v_mfma_f32_16x16x32_bf16 v[18:21], v[188:191], v[240:243], v[18:21]
	v_mfma_f32_16x16x32_bf16 v[10:13], v[204:207], v[240:243], v[10:13]
	v_mfma_f32_16x16x32_bf16 v[6:9], v[188:191], v[248:251], v[6:9]
	v_mfma_f32_16x16x32_bf16 v[2:5], v[204:207], v[248:251], v[2:5]
	s_setprio 0
	s_barrier
	s_add_i32 s11, 0, 0x18000
	v_add_u32_e32 v1, s11, v173
	s_add_i32 s14, 0, 0x1c000
	ds_read_b128 v[146:149], v1
	ds_read_b128 v[150:153], v1 offset:1024
	ds_read_b128 v[154:157], v1 offset:2048
	ds_read_b128 v[158:161], v1 offset:3072
	v_add_u32_e32 v1, s14, v173
	ds_read_b128 v[184:187], v1
	ds_read_b128 v[188:191], v1 offset:1024
	ds_read_b128 v[196:199], v1 offset:2048
	ds_read_b128 v[204:207], v1 offset:3072
	s_add_u32 s12, s68, s46
	s_addc_u32 s13, s69, s47
	s_mov_b32 m0, s28
	v_lshl_add_u64 v[192:193], s[12:13], 0, v[130:131]
	ds_read_b128 v[220:223], v182 offset:32768
	ds_read_b128 v[224:227], v182 offset:33792
	ds_read_b128 v[228:231], v182 offset:34816
	ds_read_b128 v[232:235], v182 offset:35840
	ds_read_b128 v[236:239], v182 offset:36864
	ds_read_b128 v[240:243], v182 offset:37888
	ds_read_b128 v[244:247], v182 offset:38912
	ds_read_b128 v[248:251], v182 offset:39936
	global_load_lds_dwordx4 v[192:193], off
	v_lshl_add_u64 v[192:193], s[12:13], 0, v[134:135]
	s_mov_b32 m0, s29
	s_nop 0
	global_load_lds_dwordx4 v[192:193], off
	s_waitcnt vmcnt(8)
	s_waitcnt lgkmcnt(0)
	s_barrier
	s_setprio 1
	s_waitcnt lgkmcnt(0)
	v_mfma_f32_16x16x32_bf16 v[126:129], v[146:149], v[220:223], v[126:129]
	v_mfma_f32_16x16x32_bf16 v[122:125], v[154:157], v[220:223], v[122:125]
	v_mfma_f32_16x16x32_bf16 v[118:121], v[146:149], v[228:231], v[118:121]
	v_mfma_f32_16x16x32_bf16 v[110:113], v[154:157], v[228:231], v[110:113]
	v_mfma_f32_16x16x32_bf16 v[102:105], v[146:149], v[236:239], v[102:105]
	v_mfma_f32_16x16x32_bf16 v[94:97], v[154:157], v[236:239], v[94:97]
	v_mfma_f32_16x16x32_bf16 v[86:89], v[146:149], v[244:247], v[86:89]
	v_mfma_f32_16x16x32_bf16 v[78:81], v[154:157], v[244:247], v[78:81]
	v_mfma_f32_16x16x32_bf16 v[126:129], v[150:153], v[224:227], v[126:129]
	v_mfma_f32_16x16x32_bf16 v[122:125], v[158:161], v[224:227], v[122:125]
	v_mfma_f32_16x16x32_bf16 v[118:121], v[150:153], v[232:235], v[118:121]
	v_mfma_f32_16x16x32_bf16 v[110:113], v[158:161], v[232:235], v[110:113]
	v_mfma_f32_16x16x32_bf16 v[102:105], v[150:153], v[240:243], v[102:105]
	v_mfma_f32_16x16x32_bf16 v[94:97], v[158:161], v[240:243], v[94:97]
	v_mfma_f32_16x16x32_bf16 v[86:89], v[150:153], v[248:251], v[86:89]
	v_mfma_f32_16x16x32_bf16 v[78:81], v[158:161], v[248:251], v[78:81]
	s_setprio 0
	s_setprio 1
	v_mfma_f32_16x16x32_bf16 v[114:117], v[184:187], v[220:223], v[114:117]
	v_mfma_f32_16x16x32_bf16 v[106:109], v[196:199], v[220:223], v[106:109]
	v_mfma_f32_16x16x32_bf16 v[98:101], v[184:187], v[228:231], v[98:101]
	v_mfma_f32_16x16x32_bf16 v[90:93], v[196:199], v[228:231], v[90:93]
	v_mfma_f32_16x16x32_bf16 v[82:85], v[184:187], v[236:239], v[82:85]
	v_mfma_f32_16x16x32_bf16 v[74:77], v[196:199], v[236:239], v[74:77]
	v_mfma_f32_16x16x32_bf16 v[70:73], v[184:187], v[244:247], v[70:73]
	v_mfma_f32_16x16x32_bf16 v[66:69], v[196:199], v[244:247], v[66:69]
	v_mfma_f32_16x16x32_bf16 v[114:117], v[188:191], v[224:227], v[114:117]
	v_mfma_f32_16x16x32_bf16 v[106:109], v[204:207], v[224:227], v[106:109]
	v_mfma_f32_16x16x32_bf16 v[98:101], v[188:191], v[232:235], v[98:101]
	v_mfma_f32_16x16x32_bf16 v[90:93], v[204:207], v[232:235], v[90:93]
	v_mfma_f32_16x16x32_bf16 v[82:85], v[188:191], v[240:243], v[82:85]
	v_mfma_f32_16x16x32_bf16 v[74:77], v[204:207], v[240:243], v[74:77]
	v_mfma_f32_16x16x32_bf16 v[70:73], v[188:191], v[248:251], v[70:73]
	v_mfma_f32_16x16x32_bf16 v[66:69], v[204:207], v[248:251], v[66:69]
	s_setprio 0
	s_barrier
; #define PG8_STAGE(bufoff, gbase, voff) do { _Pragma("unroll") for (int _i = 0; _i < 2; ++_i) \
;         __builtin_amdgcn_global_load_lds((const unsigned*)((const char*)(gbase) + (voff)[_i]), (LAS unsigned*)(lds + (bufoff) + ldsw + _i * 8192), 16, 0, 0); } while (0)
; #define PG8_LDA(dst, b, h) do { _Pragma("unroll") for (int m = 0; m < 4; ++m) _Pragma("unroll") for (int k = 0; k < 2; ++k) dst[m][k] = *(const LAS bf16x8*)(lds + PG8_SA(b, h) + aoff + m * 2048 + k * 1024); } while (0)
; #define PG8_MMA(ai, bj, At, Bt) do { __builtin_amdgcn_s_setprio(1); _Pragma("unroll") for (int m = 0; m < 4; ++m) _Pragma("unroll") for (int n = 0; n < 2; ++n) _Pragma("unroll") for (int k = 0; k < 2; ++k) \
;         acc[ai][bj][m][n] = __builtin_amdgcn_mfma_f32_16x16x32_bf16(Bt[n][k], At[m][k], acc[ai][bj][m][n], 0, 0, 0); __builtin_amdgcn_s_setprio(0); } while (0)
; #define PG8_WAIT_V(n) asm volatile("s_waitcnt vmcnt(" #n ")" ::: "memory")
; #define PG8_WAIT_L(n) asm volatile("s_waitcnt lgkmcnt(" #n ")" ::: "memory")
; #define PG8_BAR __builtin_amdgcn_s_barrier()
; #define PG8_SCHED __builtin_amdgcn_sched_barrier(0)
; template <int MODE> __device__ __forceinline__ void gemm_phase(LAS unsigned char* lds, const GD& g, const int tid) {
;     ...
;             PG8_WAIT_V(8); PG8_WAIT_L(0); PG8_BAR; PG8_MMA(0, 0, At, B0); PG8_MMA(0, 1, At, B1); PG8_BAR; PG8_SCHED;
;             PG8_LDA(At, 1, 1); PG8_STAGE(PG8_SB(1, 0), b3, voffB); PG8_STAGE(PG8_SB(1, 1), b3 + hsB, voffB); PG8_STAGE(PG8_SA(1, 0), a3, voffA);
;             PG8_WAIT_V(8); PG8_WAIT_L(0); PG8_BAR; PG8_MMA(1, 0, At, B0); PG8_MMA(1, 1, At, B1); PG8_BAR; PG8_SCHED;
;         }
	s_add_u32 s12, s64, s22
	s_addc_u32 s13, s65, s23
	s_add_i32 s11, s11, s25
	v_lshl_add_u64 v[192:193], s[12:13], 0, v[132:133]
	s_mov_b32 m0, s11
	ds_read_b128 v[220:223], v182 offset:49152
	ds_read_b128 v[224:227], v182 offset:50176
	ds_read_b128 v[228:231], v182 offset:51200
	ds_read_b128 v[232:235], v182 offset:52224
	ds_read_b128 v[236:239], v182 offset:53248
	ds_read_b128 v[240:243], v182 offset:54272
	ds_read_b128 v[244:247], v182 offset:55296
	ds_read_b128 v[248:251], v182 offset:56320
	global_load_lds_dwordx4 v[192:193], off
	s_add_i32 m0, s11, 0x2000
	v_lshl_add_u64 v[192:193], s[12:13], 0, v[136:137]
	s_add_u32 s12, s12, s58
	s_addc_u32 s13, s13, s59
	s_add_i32 s11, s14, s25
	global_load_lds_dwordx4 v[192:193], off
	v_lshl_add_u64 v[192:193], s[12:13], 0, v[132:133]
	s_mov_b32 m0, s11
	s_nop 0
	global_load_lds_dwordx4 v[192:193], off
	v_lshl_add_u64 v[192:193], s[12:13], 0, v[136:137]
	s_add_i32 m0, s11, 0x2000
	s_nop 0
	global_load_lds_dwordx4 v[192:193], off
	v_lshl_add_u64 v[192:193], vcc, 0, v[130:131]
	s_mov_b32 m0, s93
	s_nop 0
	global_load_lds_dwordx4 v[192:193], off
	v_lshl_add_u64 v[192:193], vcc, 0, v[134:135]
	s_mov_b32 m0, s86
	s_nop 0
	global_load_lds_dwordx4 v[192:193], off
	s_waitcnt vmcnt(8)
	s_waitcnt lgkmcnt(0)
	s_barrier
	s_setprio 1
	s_waitcnt lgkmcnt(0)
	v_mfma_f32_16x16x32_bf16 v[62:65], v[146:149], v[220:223], v[62:65]
	v_mfma_f32_16x16x32_bf16 v[58:61], v[154:157], v[220:223], v[58:61]
	v_mfma_f32_16x16x32_bf16 v[54:57], v[146:149], v[228:231], v[54:57]
	v_mfma_f32_16x16x32_bf16 v[46:49], v[154:157], v[228:231], v[46:49]
	v_mfma_f32_16x16x32_bf16 v[38:41], v[146:149], v[236:239], v[38:41]
	v_mfma_f32_16x16x32_bf16 v[30:33], v[154:157], v[236:239], v[30:33]
	v_mfma_f32_16x16x32_bf16 v[22:25], v[146:149], v[244:247], v[22:25]
	v_mfma_f32_16x16x32_bf16 v[14:17], v[154:157], v[244:247], v[14:17]
	v_mfma_f32_16x16x32_bf16 v[62:65], v[150:153], v[224:227], v[62:65]
	v_mfma_f32_16x16x32_bf16 v[58:61], v[158:161], v[224:227], v[58:61]
	v_mfma_f32_16x16x32_bf16 v[54:57], v[150:153], v[232:235], v[54:57]
	v_mfma_f32_16x16x32_bf16 v[46:49], v[158:161], v[232:235], v[46:49]
	v_mfma_f32_16x16x32_bf16 v[38:41], v[150:153], v[240:243], v[38:41]
	v_mfma_f32_16x16x32_bf16 v[30:33], v[158:161], v[240:243], v[30:33]
	v_mfma_f32_16x16x32_bf16 v[22:25], v[150:153], v[248:251], v[22:25]
	v_mfma_f32_16x16x32_bf16 v[14:17], v[158:161], v[248:251], v[14:17]
	s_setprio 0
	s_setprio 1
	v_mfma_f32_16x16x32_bf16 v[50:53], v[184:187], v[220:223], v[50:53]
	v_mfma_f32_16x16x32_bf16 v[42:45], v[196:199], v[220:223], v[42:45]
	v_mfma_f32_16x16x32_bf16 v[34:37], v[184:187], v[228:231], v[34:37]
	v_mfma_f32_16x16x32_bf16 v[26:29], v[196:199], v[228:231], v[26:29]
	v_mfma_f32_16x16x32_bf16 v[18:21], v[184:187], v[236:239], v[18:21]
	v_mfma_f32_16x16x32_bf16 v[10:13], v[196:199], v[236:239], v[10:13]
	v_mfma_f32_16x16x32_bf16 v[6:9], v[184:187], v[244:247], v[6:9]
	v_mfma_f32_16x16x32_bf16 v[2:5], v[196:199], v[244:247], v[2:5]
	v_mfma_f32_16x16x32_bf16 v[50:53], v[188:191], v[224:227], v[50:53]
	v_mfma_f32_16x16x32_bf16 v[42:45], v[204:207], v[224:227], v[42:45]
	v_mfma_f32_16x16x32_bf16 v[34:37], v[188:191], v[232:235], v[34:37]
	v_mfma_f32_16x16x32_bf16 v[26:29], v[204:207], v[232:235], v[26:29]
	v_mfma_f32_16x16x32_bf16 v[18:21], v[188:191], v[240:243], v[18:21]
	v_mfma_f32_16x16x32_bf16 v[10:13], v[204:207], v[240:243], v[10:13]
	v_mfma_f32_16x16x32_bf16 v[6:9], v[188:191], v[248:251], v[6:9]
	v_mfma_f32_16x16x32_bf16 v[2:5], v[204:207], v[248:251], v[2:5]
	s_setprio 0
	s_barrier
	s_add_u32 s8, s8, s94
	s_addc_u32 s9, s9, s95
	s_add_u32 s6, s6, s42
	s_addc_u32 s7, s7, s43
	s_cmp_ge_i32 s1, s92
	s_cbranch_scc1 .LBB0_335
	s_branch .LBB0_330

; template <int MODE> __device__ __forceinline__ void gemm_epilogue(f32x4 (&acc)[2][2][4][2], const GD& g, const pg8::Unit& u, int wr, int wc, int fr, int fq, LAS unsigned char* lds, const float (&rsv)[2][4]) {
;     ...
;         } else if (wc == 0 && fq < 2) {
;             float* FL = (float*)g.o3; const float* bfv = g.f0;
; #pragma unroll
;             for (int ai = 0; ai < 2; ++ai)
; #pragma unroll
;                 for (int m = 0; m < 4; ++m) { const int row = rt + ai * 128 + m * 16;
; #pragma unroll
;                     for (int n = 0; n < 2; ++n) { f32x4 v = acc[ai][0][m][n];
; #pragma unroll
;                         for (int j = 0; j < 4; ++j) { const int hh = 8 * fq + 4 * n + j; const float x = v[j] + bfv[hh];
;                             FL[(size_t)((row >> 12) * 16 + hh) * 4096 + (row & 4095)] = fminf(x, 0.f) - __logf(1.f + __expf(-fabsf(x))); } } }
.LBB0_339:
	s_lshl_b32 s0, s0, 8
	s_add_i32 s0, s0, s17
	v_or_b32_e32 v1, s0, v162
	s_cmp_gt_i32 s24, 23
	s_mov_b64 s[2:3], -1
	s_cbranch_scc0 .LBB0_344
	s_and_saveexec_b64 s[68:69], s[74:75]
	s_cbranch_execz .LBB0_342
	flat_load_dword v148, v[140:141]
	v_and_b32_e32 v146, 0xfcf, v1
	v_readlane_b32 s2, v254, 46
	v_mov_b32_e32 v147, v0
	v_lshlrev_b32_e32 v146, 2, v146
	v_readlane_b32 s3, v254, 47
	s_ashr_i32 s1, s0, 8
	s_and_b32 s1, s1, -16
	v_lshl_add_u64 v[160:161], s[2:3], 0, v[146:147]
	s_waitcnt vmcnt(0) lgkmcnt(0)
	v_add_f32_e32 v148, v126, v148
	v_mul_f32_e64 v146, |v148|, s18
	v_exp_f32_e32 v149, v146
	v_or_b32_e32 v146, s1, v172
	v_ashrrev_i32_e32 v147, 31, v146
	v_lshlrev_b64 v[146:147], 14, v[146:147]
	v_add_f32_e32 v149, 1.0, v149
	v_cmp_gt_f32_e32 vcc, s80, v149
	v_min_f32_e32 v148, 0, v148
	v_lshl_add_u64 v[146:147], v[160:161], 0, v[146:147]
	v_cndmask_b32_e64 v150, 0, 32, vcc
	v_ldexp_f32 v149, v149, v150
	v_log_f32_e32 v149, v149
	v_cndmask_b32_e32 v150, 0, v214, vcc
	v_mul_f32_e32 v151, 0x3f317217, v149
	v_fma_f32 v151, v149, s85, -v151
	v_fmac_f32_e32 v151, 0x3377d1cf, v149
	v_fmac_f32_e32 v151, 0x3f317217, v149
	v_cmp_lt_f32_e64 vcc, |v149|, s55
	s_nop 1
	v_cndmask_b32_e32 v149, v149, v151, vcc
	v_sub_f32_e32 v149, v149, v150
	v_sub_f32_e32 v148, v148, v149
	global_store_dword v[146:147], v148, off
	flat_load_dword v148, v[140:141] offset:4
	s_waitcnt vmcnt(0) lgkmcnt(0)
	v_add_f32_e32 v150, v127, v148
	v_mul_f32_e64 v148, |v150|, s18
	v_exp_f32_e32 v151, v148
	v_or_b32_e32 v148, s1, v174
	v_ashrrev_i32_e32 v149, 31, v148
	v_lshlrev_b64 v[148:149], 14, v[148:149]
	v_add_f32_e32 v151, 1.0, v151
	v_cmp_gt_f32_e32 vcc, s80, v151
	v_min_f32_e32 v150, 0, v150
	v_lshl_add_u64 v[148:149], v[160:161], 0, v[148:149]
	v_cndmask_b32_e64 v152, 0, 32, vcc
	v_ldexp_f32 v151, v151, v152
	v_log_f32_e32 v151, v151
	v_cndmask_b32_e32 v152, 0, v214, vcc
	v_mul_f32_e32 v153, 0x3f317217, v151
	v_fma_f32 v153, v151, s85, -v153
	v_fmac_f32_e32 v153, 0x3377d1cf, v151
	v_fmac_f32_e32 v153, 0x3f317217, v151
	v_cmp_lt_f32_e64 vcc, |v151|, s55
	s_nop 1
	v_cndmask_b32_e32 v151, v151, v153, vcc
	v_sub_f32_e32 v151, v151, v152
	v_sub_f32_e32 v150, v150, v151
	global_store_dword v[148:149], v150, off
	flat_load_dword v150, v[140:141] offset:8
	s_waitcnt vmcnt(0) lgkmcnt(0)
	v_add_f32_e32 v152, v128, v150
	v_mul_f32_e64 v150, |v152|, s18
	v_exp_f32_e32 v153, v150
	v_or_b32_e32 v150, s1, v175
	v_ashrrev_i32_e32 v151, 31, v150
	v_lshlrev_b64 v[150:151], 14, v[150:151]
	v_add_f32_e32 v153, 1.0, v153
	v_cmp_gt_f32_e32 vcc, s80, v153
	v_min_f32_e32 v152, 0, v152
	v_lshl_add_u64 v[150:151], v[160:161], 0, v[150:151]
	v_cndmask_b32_e64 v154, 0, 32, vcc
	v_ldexp_f32 v153, v153, v154
	v_log_f32_e32 v153, v153
	v_cndmask_b32_e32 v154, 0, v214, vcc
	v_mul_f32_e32 v155, 0x3f317217, v153
	v_fma_f32 v155, v153, s85, -v155
	v_fmac_f32_e32 v155, 0x3377d1cf, v153
	v_fmac_f32_e32 v155, 0x3f317217, v153
	v_cmp_lt_f32_e64 vcc, |v153|, s55
	s_nop 1
	v_cndmask_b32_e32 v153, v153, v155, vcc
	v_sub_f32_e32 v153, v153, v154
	v_sub_f32_e32 v152, v152, v153
	global_store_dword v[150:151], v152, off
	flat_load_dword v152, v[140:141] offset:12
	s_waitcnt vmcnt(0) lgkmcnt(0)
	v_add_f32_e32 v154, v129, v152
	v_mul_f32_e64 v152, |v154|, s18
	v_exp_f32_e32 v155, v152
	v_or_b32_e32 v152, s1, v176
	v_ashrrev_i32_e32 v153, 31, v152
	v_lshlrev_b64 v[152:153], 14, v[152:153]
	v_add_f32_e32 v155, 1.0, v155
	v_cmp_gt_f32_e32 vcc, s80, v155
	v_min_f32_e32 v154, 0, v154
	v_lshl_add_u64 v[152:153], v[160:161], 0, v[152:153]
	v_cndmask_b32_e64 v156, 0, 32, vcc
	v_ldexp_f32 v155, v155, v156
	v_log_f32_e32 v155, v155
	v_cndmask_b32_e32 v156, 0, v214, vcc
	v_mul_f32_e32 v157, 0x3f317217, v155
	v_fma_f32 v157, v155, s85, -v157
	v_fmac_f32_e32 v157, 0x3377d1cf, v155
	v_fmac_f32_e32 v157, 0x3f317217, v155
	v_cmp_lt_f32_e64 vcc, |v155|, s55
	s_nop 1
	v_cndmask_b32_e32 v155, v155, v157, vcc
	v_sub_f32_e32 v155, v155, v156
	v_sub_f32_e32 v154, v154, v155
	global_store_dword v[152:153], v154, off
	flat_load_dword v154, v[140:141] offset:16
	s_waitcnt vmcnt(0) lgkmcnt(0)
	v_add_f32_e32 v156, v122, v154
	v_mul_f32_e64 v154, |v156|, s18
	v_exp_f32_e32 v157, v154
	v_or_b32_e32 v154, s1, v177
	v_ashrrev_i32_e32 v155, 31, v154
	v_lshlrev_b64 v[154:155], 14, v[154:155]
	v_add_f32_e32 v157, 1.0, v157
	v_cmp_gt_f32_e32 vcc, s80, v157
	v_min_f32_e32 v156, 0, v156
	v_lshl_add_u64 v[154:155], v[160:161], 0, v[154:155]
	v_cndmask_b32_e64 v158, 0, 32, vcc
	v_ldexp_f32 v157, v157, v158
	v_log_f32_e32 v157, v157
	v_cndmask_b32_e32 v158, 0, v214, vcc
	v_mul_f32_e32 v159, 0x3f317217, v157
	v_fma_f32 v159, v157, s85, -v159
	v_fmac_f32_e32 v159, 0x3377d1cf, v157
	v_fmac_f32_e32 v159, 0x3f317217, v157
	v_cmp_lt_f32_e64 vcc, |v157|, s55
	s_nop 1
	v_cndmask_b32_e32 v157, v157, v159, vcc
	v_sub_f32_e32 v157, v157, v158
	v_sub_f32_e32 v156, v156, v157
	global_store_dword v[154:155], v156, off
	flat_load_dword v156, v[140:141] offset:20
	s_waitcnt vmcnt(0) lgkmcnt(0)
	v_add_f32_e32 v158, v123, v156
	v_mul_f32_e64 v156, |v158|, s18
	v_exp_f32_e32 v159, v156
	v_or_b32_e32 v156, s1, v178
	v_ashrrev_i32_e32 v157, 31, v156
	v_lshlrev_b64 v[156:157], 14, v[156:157]
	v_add_f32_e32 v159, 1.0, v159
	v_cmp_gt_f32_e32 vcc, s80, v159
	v_min_f32_e32 v158, 0, v158
	v_lshl_add_u64 v[156:157], v[160:161], 0, v[156:157]
	v_cndmask_b32_e64 v183, 0, 32, vcc
	v_ldexp_f32 v159, v159, v183
	v_log_f32_e32 v159, v159
	v_cndmask_b32_e32 v183, 0, v214, vcc
	v_mul_f32_e32 v184, 0x3f317217, v159
	v_fma_f32 v184, v159, s85, -v184
	v_fmac_f32_e32 v184, 0x3377d1cf, v159
	v_fmac_f32_e32 v184, 0x3f317217, v159
	v_cmp_lt_f32_e64 vcc, |v159|, s55
	s_nop 1
	v_cndmask_b32_e32 v159, v159, v184, vcc
	v_sub_f32_e32 v159, v159, v183
	v_sub_f32_e32 v158, v158, v159
	global_store_dword v[156:157], v158, off
	flat_load_dword v158, v[140:141] offset:24
	s_waitcnt vmcnt(0) lgkmcnt(0)
; template <int MODE> __device__ __forceinline__ void gemm_epilogue(f32x4 (&acc)[2][2][4][2], const GD& g, const pg8::Unit& u, int wr, int wc, int fr, int fq, LAS unsigned char* lds, const float (&rsv)[2][4]) {
;     ...
;         } else if (wc == 0 && fq < 2) {
;             float* FL = (float*)g.o3; const float* bfv = g.f0;
; #pragma unroll
;             for (int ai = 0; ai < 2; ++ai)
; #pragma unroll
;                 for (int m = 0; m < 4; ++m) { const int row = rt + ai * 128 + m * 16;
; #pragma unroll
;                     for (int n = 0; n < 2; ++n) { f32x4 v = acc[ai][0][m][n];
; #pragma unroll
;                         for (int j = 0; j < 4; ++j) { const int hh = 8 * fq + 4 * n + j; const float x = v[j] + bfv[hh];
;                             FL[(size_t)((row >> 12) * 16 + hh) * 4096 + (row & 4095)] = fminf(x, 0.f) - __logf(1.f + __expf(-fabsf(x))); } } }
	v_add_f32_e32 v183, v124, v158
	v_mul_f32_e64 v158, |v183|, s18
	v_exp_f32_e32 v184, v158
	v_or_b32_e32 v158, s1, v179
	v_ashrrev_i32_e32 v159, 31, v158
	v_lshlrev_b64 v[158:159], 14, v[158:159]
	v_add_f32_e32 v184, 1.0, v184
	v_cmp_gt_f32_e32 vcc, s80, v184
	v_min_f32_e32 v183, 0, v183
	v_lshl_add_u64 v[158:159], v[160:161], 0, v[158:159]
	v_cndmask_b32_e64 v185, 0, 32, vcc
	v_ldexp_f32 v184, v184, v185
	v_log_f32_e32 v184, v184
	v_cndmask_b32_e32 v185, 0, v214, vcc
	v_mul_f32_e32 v186, 0x3f317217, v184
	v_fma_f32 v186, v184, s85, -v186
	v_fmac_f32_e32 v186, 0x3377d1cf, v184
	v_fmac_f32_e32 v186, 0x3f317217, v184
	v_cmp_lt_f32_e64 vcc, |v184|, s55
	s_nop 1
	v_cndmask_b32_e32 v184, v184, v186, vcc
	v_sub_f32_e32 v184, v184, v185
	v_sub_f32_e32 v183, v183, v184
	global_store_dword v[158:159], v183, off
	flat_load_dword v183, v[140:141] offset:28
	s_waitcnt vmcnt(0) lgkmcnt(0)
	v_add_f32_e32 v183, v125, v183
	v_mul_f32_e64 v184, |v183|, s18
	v_exp_f32_e32 v186, v184
	v_or_b32_e32 v184, s1, v180
	v_ashrrev_i32_e32 v185, 31, v184
	v_lshlrev_b64 v[184:185], 14, v[184:185]
	v_add_f32_e32 v186, 1.0, v186
	v_cmp_gt_f32_e32 vcc, s80, v186
	v_lshl_add_u64 v[160:161], v[160:161], 0, v[184:185]
	v_min_f32_e32 v183, 0, v183
	v_cndmask_b32_e64 v187, 0, 32, vcc
	v_ldexp_f32 v186, v186, v187
	v_log_f32_e32 v186, v186
	v_cndmask_b32_e32 v184, 0, v214, vcc
	v_mul_f32_e32 v185, 0x3f317217, v186
	v_fma_f32 v185, v186, s85, -v185
	v_fmac_f32_e32 v185, 0x3377d1cf, v186
	v_fmac_f32_e32 v185, 0x3f317217, v186
	v_cmp_lt_f32_e64 vcc, |v186|, s55
	s_nop 1
	v_cndmask_b32_e32 v185, v186, v185, vcc
	v_sub_f32_e32 v184, v185, v184
	v_sub_f32_e32 v183, v183, v184
	global_store_dword v[160:161], v183, off
	flat_load_dword v183, v[140:141]
	s_waitcnt vmcnt(0) lgkmcnt(0)
	v_add_f32_e32 v183, v118, v183
	v_mul_f32_e64 v184, |v183|, s18
	v_exp_f32_e32 v184, v184
	v_min_f32_e32 v183, 0, v183
	v_add_f32_e32 v184, 1.0, v184
	v_cmp_gt_f32_e32 vcc, s80, v184
	s_nop 1
	v_cndmask_b32_e64 v185, 0, 32, vcc
	v_ldexp_f32 v184, v184, v185
	v_log_f32_e32 v184, v184
	v_cndmask_b32_e32 v185, 0, v214, vcc
	v_mul_f32_e32 v186, 0x3f317217, v184
	v_fma_f32 v186, v184, s85, -v186
	v_fmac_f32_e32 v186, 0x3377d1cf, v184
	v_fmac_f32_e32 v186, 0x3f317217, v184
	v_cmp_lt_f32_e64 vcc, |v184|, s55
	s_nop 1
	v_cndmask_b32_e32 v184, v184, v186, vcc
	v_sub_f32_e32 v184, v184, v185
	v_sub_f32_e32 v183, v183, v184
	global_store_dword v[146:147], v183, off offset:64
	flat_load_dword v183, v[140:141] offset:4
	s_waitcnt vmcnt(0) lgkmcnt(0)
	v_add_f32_e32 v183, v119, v183
	v_mul_f32_e64 v184, |v183|, s18
	v_exp_f32_e32 v184, v184
	v_min_f32_e32 v183, 0, v183
	v_add_f32_e32 v184, 1.0, v184
	v_cmp_gt_f32_e32 vcc, s80, v184
	s_nop 1
	v_cndmask_b32_e64 v185, 0, 32, vcc
	v_ldexp_f32 v184, v184, v185
	v_log_f32_e32 v184, v184
	v_cndmask_b32_e32 v185, 0, v214, vcc
	v_mul_f32_e32 v186, 0x3f317217, v184
	v_fma_f32 v186, v184, s85, -v186
	v_fmac_f32_e32 v186, 0x3377d1cf, v184
	v_fmac_f32_e32 v186, 0x3f317217, v184
	v_cmp_lt_f32_e64 vcc, |v184|, s55
	s_nop 1
	v_cndmask_b32_e32 v184, v184, v186, vcc
	v_sub_f32_e32 v184, v184, v185
	v_sub_f32_e32 v183, v183, v184
	global_store_dword v[148:149], v183, off offset:64
	flat_load_dword v183, v[140:141] offset:8
	s_waitcnt vmcnt(0) lgkmcnt(0)
	v_add_f32_e32 v183, v120, v183
	v_mul_f32_e64 v184, |v183|, s18
	v_exp_f32_e32 v184, v184
	v_min_f32_e32 v183, 0, v183
	v_add_f32_e32 v184, 1.0, v184
	v_cmp_gt_f32_e32 vcc, s80, v184
	s_nop 1
	v_cndmask_b32_e64 v185, 0, 32, vcc
	v_ldexp_f32 v184, v184, v185
	v_log_f32_e32 v184, v184
	v_cndmask_b32_e32 v185, 0, v214, vcc
	v_mul_f32_e32 v186, 0x3f317217, v184
	v_fma_f32 v186, v184, s85, -v186
	v_fmac_f32_e32 v186, 0x3377d1cf, v184
	v_fmac_f32_e32 v186, 0x3f317217, v184
	v_cmp_lt_f32_e64 vcc, |v184|, s55
	s_nop 1
	v_cndmask_b32_e32 v184, v184, v186, vcc
	v_sub_f32_e32 v184, v184, v185
	v_sub_f32_e32 v183, v183, v184
	global_store_dword v[150:151], v183, off offset:64
	flat_load_dword v183, v[140:141] offset:12
	s_waitcnt vmcnt(0) lgkmcnt(0)
	v_add_f32_e32 v183, v121, v183
	v_mul_f32_e64 v184, |v183|, s18
	v_exp_f32_e32 v184, v184
	v_min_f32_e32 v183, 0, v183
	v_add_f32_e32 v184, 1.0, v184
	v_cmp_gt_f32_e32 vcc, s80, v184
	s_nop 1
	v_cndmask_b32_e64 v185, 0, 32, vcc
	v_ldexp_f32 v184, v184, v185
	v_log_f32_e32 v184, v184
	v_cndmask_b32_e32 v185, 0, v214, vcc
	v_mul_f32_e32 v186, 0x3f317217, v184
	v_fma_f32 v186, v184, s85, -v186
	v_fmac_f32_e32 v186, 0x3377d1cf, v184
	v_fmac_f32_e32 v186, 0x3f317217, v184
	v_cmp_lt_f32_e64 vcc, |v184|, s55
	s_nop 1
	v_cndmask_b32_e32 v184, v184, v186, vcc
	v_sub_f32_e32 v184, v184, v185
	v_sub_f32_e32 v183, v183, v184
	global_store_dword v[152:153], v183, off offset:64
	flat_load_dword v183, v[140:141] offset:16
	s_waitcnt vmcnt(0) lgkmcnt(0)
	v_add_f32_e32 v183, v110, v183
	v_mul_f32_e64 v184, |v183|, s18
	v_exp_f32_e32 v184, v184
	v_min_f32_e32 v183, 0, v183
	v_add_f32_e32 v184, 1.0, v184
	v_cmp_gt_f32_e32 vcc, s80, v184
	s_nop 1
	v_cndmask_b32_e64 v185, 0, 32, vcc
	v_ldexp_f32 v184, v184, v185
	v_log_f32_e32 v184, v184
	v_cndmask_b32_e32 v185, 0, v214, vcc
	v_mul_f32_e32 v186, 0x3f317217, v184
	v_fma_f32 v186, v184, s85, -v186
	v_fmac_f32_e32 v186, 0x3377d1cf, v184
	v_fmac_f32_e32 v186, 0x3f317217, v184
	v_cmp_lt_f32_e64 vcc, |v184|, s55
	s_nop 1
	v_cndmask_b32_e32 v184, v184, v186, vcc
	v_sub_f32_e32 v184, v184, v185
	v_sub_f32_e32 v183, v183, v184
	global_store_dword v[154:155], v183, off offset:64
	flat_load_dword v183, v[140:141] offset:20
	s_waitcnt vmcnt(0) lgkmcnt(0)
; template <int MODE> __device__ __forceinline__ void gemm_epilogue(f32x4 (&acc)[2][2][4][2], const GD& g, const pg8::Unit& u, int wr, int wc, int fr, int fq, LAS unsigned char* lds, const float (&rsv)[2][4]) {
;     ...
;         } else if (wc == 0 && fq < 2) {
;             float* FL = (float*)g.o3; const float* bfv = g.f0;
; #pragma unroll
;             for (int ai = 0; ai < 2; ++ai)
; #pragma unroll
;                 for (int m = 0; m < 4; ++m) { const int row = rt + ai * 128 + m * 16;
; #pragma unroll
;                     for (int n = 0; n < 2; ++n) { f32x4 v = acc[ai][0][m][n];
; #pragma unroll
;                         for (int j = 0; j < 4; ++j) { const int hh = 8 * fq + 4 * n + j; const float x = v[j] + bfv[hh];
;                             FL[(size_t)((row >> 12) * 16 + hh) * 4096 + (row & 4095)] = fminf(x, 0.f) - __logf(1.f + __expf(-fabsf(x))); } } }
	v_add_f32_e32 v183, v111, v183
	v_mul_f32_e64 v184, |v183|, s18
	v_exp_f32_e32 v184, v184
	v_min_f32_e32 v183, 0, v183
	v_add_f32_e32 v184, 1.0, v184
	v_cmp_gt_f32_e32 vcc, s80, v184
	s_nop 1
	v_cndmask_b32_e64 v185, 0, 32, vcc
	v_ldexp_f32 v184, v184, v185
	v_log_f32_e32 v184, v184
	v_cndmask_b32_e32 v185, 0, v214, vcc
	v_mul_f32_e32 v186, 0x3f317217, v184
	v_fma_f32 v186, v184, s85, -v186
	v_fmac_f32_e32 v186, 0x3377d1cf, v184
	v_fmac_f32_e32 v186, 0x3f317217, v184
	v_cmp_lt_f32_e64 vcc, |v184|, s55
	s_nop 1
	v_cndmask_b32_e32 v184, v184, v186, vcc
	v_sub_f32_e32 v184, v184, v185
	v_sub_f32_e32 v183, v183, v184
	global_store_dword v[156:157], v183, off offset:64
	flat_load_dword v183, v[140:141] offset:24
	s_waitcnt vmcnt(0) lgkmcnt(0)
	v_add_f32_e32 v183, v112, v183
	v_mul_f32_e64 v184, |v183|, s18
	v_exp_f32_e32 v184, v184
	v_min_f32_e32 v183, 0, v183
	v_add_f32_e32 v184, 1.0, v184
	v_cmp_gt_f32_e32 vcc, s80, v184
	s_nop 1
	v_cndmask_b32_e64 v185, 0, 32, vcc
	v_ldexp_f32 v184, v184, v185
	v_log_f32_e32 v184, v184
	v_cndmask_b32_e32 v185, 0, v214, vcc
	v_mul_f32_e32 v186, 0x3f317217, v184
	v_fma_f32 v186, v184, s85, -v186
	v_fmac_f32_e32 v186, 0x3377d1cf, v184
	v_fmac_f32_e32 v186, 0x3f317217, v184
	v_cmp_lt_f32_e64 vcc, |v184|, s55
	s_nop 1
	v_cndmask_b32_e32 v184, v184, v186, vcc
	v_sub_f32_e32 v184, v184, v185
	v_sub_f32_e32 v183, v183, v184
	global_store_dword v[158:159], v183, off offset:64
	flat_load_dword v183, v[140:141] offset:28
	s_waitcnt vmcnt(0) lgkmcnt(0)
	v_add_f32_e32 v183, v113, v183
	v_mul_f32_e64 v184, |v183|, s18
	v_exp_f32_e32 v184, v184
	v_min_f32_e32 v183, 0, v183
	v_add_f32_e32 v184, 1.0, v184
	v_cmp_gt_f32_e32 vcc, s80, v184
	s_nop 1
	v_cndmask_b32_e64 v185, 0, 32, vcc
	v_ldexp_f32 v184, v184, v185
	v_log_f32_e32 v184, v184
	v_cndmask_b32_e32 v185, 0, v214, vcc
	v_mul_f32_e32 v186, 0x3f317217, v184
	v_fma_f32 v186, v184, s85, -v186
	v_fmac_f32_e32 v186, 0x3377d1cf, v184
	v_fmac_f32_e32 v186, 0x3f317217, v184
	v_cmp_lt_f32_e64 vcc, |v184|, s55
	s_nop 1
	v_cndmask_b32_e32 v184, v184, v186, vcc
	v_sub_f32_e32 v184, v184, v185
	v_sub_f32_e32 v183, v183, v184
	global_store_dword v[160:161], v183, off offset:64
	flat_load_dword v183, v[140:141]
	s_waitcnt vmcnt(0) lgkmcnt(0)
	v_add_f32_e32 v183, v102, v183
	v_mul_f32_e64 v184, |v183|, s18
	v_exp_f32_e32 v184, v184
	v_min_f32_e32 v183, 0, v183
	v_add_f32_e32 v184, 1.0, v184
	v_cmp_gt_f32_e32 vcc, s80, v184
	s_nop 1
	v_cndmask_b32_e64 v185, 0, 32, vcc
	v_ldexp_f32 v184, v184, v185
	v_log_f32_e32 v184, v184
	v_cndmask_b32_e32 v185, 0, v214, vcc
	v_mul_f32_e32 v186, 0x3f317217, v184
	v_fma_f32 v186, v184, s85, -v186
	v_fmac_f32_e32 v186, 0x3377d1cf, v184
	v_fmac_f32_e32 v186, 0x3f317217, v184
	v_cmp_lt_f32_e64 vcc, |v184|, s55
	s_nop 1
	v_cndmask_b32_e32 v184, v184, v186, vcc
	v_sub_f32_e32 v184, v184, v185
	v_sub_f32_e32 v183, v183, v184
	global_store_dword v[146:147], v183, off offset:128
	flat_load_dword v183, v[140:141] offset:4
	s_waitcnt vmcnt(0) lgkmcnt(0)
	v_add_f32_e32 v183, v103, v183
	v_mul_f32_e64 v184, |v183|, s18
	v_exp_f32_e32 v184, v184
	v_min_f32_e32 v183, 0, v183
	v_add_f32_e32 v184, 1.0, v184
	v_cmp_gt_f32_e32 vcc, s80, v184
	s_nop 1
	v_cndmask_b32_e64 v185, 0, 32, vcc
	v_ldexp_f32 v184, v184, v185
	v_log_f32_e32 v184, v184
	v_cndmask_b32_e32 v185, 0, v214, vcc
	v_mul_f32_e32 v186, 0x3f317217, v184
	v_fma_f32 v186, v184, s85, -v186
	v_fmac_f32_e32 v186, 0x3377d1cf, v184
	v_fmac_f32_e32 v186, 0x3f317217, v184
	v_cmp_lt_f32_e64 vcc, |v184|, s55
	s_nop 1
	v_cndmask_b32_e32 v184, v184, v186, vcc
	v_sub_f32_e32 v184, v184, v185
	v_sub_f32_e32 v183, v183, v184
	global_store_dword v[148:149], v183, off offset:128
	flat_load_dword v183, v[140:141] offset:8
	s_waitcnt vmcnt(0) lgkmcnt(0)
	v_add_f32_e32 v183, v104, v183
	v_mul_f32_e64 v184, |v183|, s18
	v_exp_f32_e32 v184, v184
	v_min_f32_e32 v183, 0, v183
	v_add_f32_e32 v184, 1.0, v184
	v_cmp_gt_f32_e32 vcc, s80, v184
	s_nop 1
	v_cndmask_b32_e64 v185, 0, 32, vcc
	v_ldexp_f32 v184, v184, v185
	v_log_f32_e32 v184, v184
	v_cndmask_b32_e32 v185, 0, v214, vcc
	v_mul_f32_e32 v186, 0x3f317217, v184
	v_fma_f32 v186, v184, s85, -v186
	v_fmac_f32_e32 v186, 0x3377d1cf, v184
	v_fmac_f32_e32 v186, 0x3f317217, v184
	v_cmp_lt_f32_e64 vcc, |v184|, s55
	s_nop 1
	v_cndmask_b32_e32 v184, v184, v186, vcc
	v_sub_f32_e32 v184, v184, v185
	v_sub_f32_e32 v183, v183, v184
	global_store_dword v[150:151], v183, off offset:128
	flat_load_dword v183, v[140:141] offset:12
	s_waitcnt vmcnt(0) lgkmcnt(0)
	v_add_f32_e32 v183, v105, v183
	v_mul_f32_e64 v184, |v183|, s18
	v_exp_f32_e32 v184, v184
	v_min_f32_e32 v183, 0, v183
	v_add_f32_e32 v184, 1.0, v184
	v_cmp_gt_f32_e32 vcc, s80, v184
	s_nop 1
	v_cndmask_b32_e64 v185, 0, 32, vcc
	v_ldexp_f32 v184, v184, v185
	v_log_f32_e32 v184, v184
	v_cndmask_b32_e32 v185, 0, v214, vcc
	v_mul_f32_e32 v186, 0x3f317217, v184
	v_fma_f32 v186, v184, s85, -v186
	v_fmac_f32_e32 v186, 0x3377d1cf, v184
	v_fmac_f32_e32 v186, 0x3f317217, v184
	v_cmp_lt_f32_e64 vcc, |v184|, s55
	s_nop 1
	v_cndmask_b32_e32 v184, v184, v186, vcc
	v_sub_f32_e32 v184, v184, v185
	v_sub_f32_e32 v183, v183, v184
	global_store_dword v[152:153], v183, off offset:128
	flat_load_dword v183, v[140:141] offset:16
	s_waitcnt vmcnt(0) lgkmcnt(0)
	v_add_f32_e32 v183, v94, v183
	v_mul_f32_e64 v184, |v183|, s18
	v_exp_f32_e32 v184, v184
	v_min_f32_e32 v183, 0, v183
	v_add_f32_e32 v184, 1.0, v184
	v_cmp_gt_f32_e32 vcc, s80, v184
	s_nop 1
	v_cndmask_b32_e64 v185, 0, 32, vcc
	v_ldexp_f32 v184, v184, v185
	v_log_f32_e32 v184, v184
	v_cndmask_b32_e32 v185, 0, v214, vcc
	v_mul_f32_e32 v186, 0x3f317217, v184
	v_fma_f32 v186, v184, s85, -v186
	v_fmac_f32_e32 v186, 0x3377d1cf, v184
	v_fmac_f32_e32 v186, 0x3f317217, v184
	v_cmp_lt_f32_e64 vcc, |v184|, s55
	s_nop 1
	v_cndmask_b32_e32 v184, v184, v186, vcc
	v_sub_f32_e32 v184, v184, v185
	v_sub_f32_e32 v183, v183, v184
	global_store_dword v[154:155], v183, off offset:128
	flat_load_dword v183, v[140:141] offset:20
	s_waitcnt vmcnt(0) lgkmcnt(0)
; template <int MODE> __device__ __forceinline__ void gemm_epilogue(f32x4 (&acc)[2][2][4][2], const GD& g, const pg8::Unit& u, int wr, int wc, int fr, int fq, LAS unsigned char* lds, const float (&rsv)[2][4]) {
;     ...
;         } else if (wc == 0 && fq < 2) {
;             float* FL = (float*)g.o3; const float* bfv = g.f0;
; #pragma unroll
;             for (int ai = 0; ai < 2; ++ai)
; #pragma unroll
;                 for (int m = 0; m < 4; ++m) { const int row = rt + ai * 128 + m * 16;
; #pragma unroll
;                     for (int n = 0; n < 2; ++n) { f32x4 v = acc[ai][0][m][n];
; #pragma unroll
;                         for (int j = 0; j < 4; ++j) { const int hh = 8 * fq + 4 * n + j; const float x = v[j] + bfv[hh];
;                             FL[(size_t)((row >> 12) * 16 + hh) * 4096 + (row & 4095)] = fminf(x, 0.f) - __logf(1.f + __expf(-fabsf(x))); } } }
	v_add_f32_e32 v183, v95, v183
	v_mul_f32_e64 v184, |v183|, s18
	v_exp_f32_e32 v184, v184
	v_min_f32_e32 v183, 0, v183
	v_add_f32_e32 v184, 1.0, v184
	v_cmp_gt_f32_e32 vcc, s80, v184
	s_nop 1
	v_cndmask_b32_e64 v185, 0, 32, vcc
	v_ldexp_f32 v184, v184, v185
	v_log_f32_e32 v184, v184
	v_cndmask_b32_e32 v185, 0, v214, vcc
	v_mul_f32_e32 v186, 0x3f317217, v184
	v_fma_f32 v186, v184, s85, -v186
	v_fmac_f32_e32 v186, 0x3377d1cf, v184
	v_fmac_f32_e32 v186, 0x3f317217, v184
	v_cmp_lt_f32_e64 vcc, |v184|, s55
	s_nop 1
	v_cndmask_b32_e32 v184, v184, v186, vcc
	v_sub_f32_e32 v184, v184, v185
	v_sub_f32_e32 v183, v183, v184
	global_store_dword v[156:157], v183, off offset:128
	flat_load_dword v183, v[140:141] offset:24
	s_waitcnt vmcnt(0) lgkmcnt(0)
	v_add_f32_e32 v183, v96, v183
	v_mul_f32_e64 v184, |v183|, s18
	v_exp_f32_e32 v184, v184
	v_min_f32_e32 v183, 0, v183
	v_add_f32_e32 v184, 1.0, v184
	v_cmp_gt_f32_e32 vcc, s80, v184
	s_nop 1
	v_cndmask_b32_e64 v185, 0, 32, vcc
	v_ldexp_f32 v184, v184, v185
	v_log_f32_e32 v184, v184
	v_cndmask_b32_e32 v185, 0, v214, vcc
	v_mul_f32_e32 v186, 0x3f317217, v184
	v_fma_f32 v186, v184, s85, -v186
	v_fmac_f32_e32 v186, 0x3377d1cf, v184
	v_fmac_f32_e32 v186, 0x3f317217, v184
	v_cmp_lt_f32_e64 vcc, |v184|, s55
	s_nop 1
	v_cndmask_b32_e32 v184, v184, v186, vcc
	v_sub_f32_e32 v184, v184, v185
	v_sub_f32_e32 v183, v183, v184
	global_store_dword v[158:159], v183, off offset:128
	flat_load_dword v183, v[140:141] offset:28
	s_waitcnt vmcnt(0) lgkmcnt(0)
	v_add_f32_e32 v183, v97, v183
	v_mul_f32_e64 v184, |v183|, s18
	v_exp_f32_e32 v184, v184
	v_min_f32_e32 v183, 0, v183
	v_add_f32_e32 v184, 1.0, v184
	v_cmp_gt_f32_e32 vcc, s80, v184
	s_nop 1
	v_cndmask_b32_e64 v185, 0, 32, vcc
	v_ldexp_f32 v184, v184, v185
	v_log_f32_e32 v184, v184
	v_cndmask_b32_e32 v185, 0, v214, vcc
	v_mul_f32_e32 v186, 0x3f317217, v184
	v_fma_f32 v186, v184, s85, -v186
	v_fmac_f32_e32 v186, 0x3377d1cf, v184
	v_fmac_f32_e32 v186, 0x3f317217, v184
	v_cmp_lt_f32_e64 vcc, |v184|, s55
	s_nop 1
	v_cndmask_b32_e32 v184, v184, v186, vcc
	v_sub_f32_e32 v184, v184, v185
	v_sub_f32_e32 v183, v183, v184
	global_store_dword v[160:161], v183, off offset:128
	flat_load_dword v183, v[140:141]
	s_waitcnt vmcnt(0) lgkmcnt(0)
	v_add_f32_e32 v183, v86, v183
	v_mul_f32_e64 v184, |v183|, s18
	v_exp_f32_e32 v184, v184
	v_min_f32_e32 v183, 0, v183
	v_add_f32_e32 v184, 1.0, v184
	v_cmp_gt_f32_e32 vcc, s80, v184
	s_nop 1
	v_cndmask_b32_e64 v185, 0, 32, vcc
	v_ldexp_f32 v184, v184, v185
	v_log_f32_e32 v184, v184
	v_cndmask_b32_e32 v185, 0, v214, vcc
	v_mul_f32_e32 v186, 0x3f317217, v184
	v_fma_f32 v186, v184, s85, -v186
	v_fmac_f32_e32 v186, 0x3377d1cf, v184
	v_fmac_f32_e32 v186, 0x3f317217, v184
	v_cmp_lt_f32_e64 vcc, |v184|, s55
	s_nop 1
	v_cndmask_b32_e32 v184, v184, v186, vcc
	v_sub_f32_e32 v184, v184, v185
	v_sub_f32_e32 v183, v183, v184
	global_store_dword v[146:147], v183, off offset:192
	flat_load_dword v146, v[140:141] offset:4
	s_waitcnt vmcnt(0) lgkmcnt(0)
	v_add_f32_e32 v146, v87, v146
	v_mul_f32_e64 v147, |v146|, s18
	v_exp_f32_e32 v147, v147
	v_min_f32_e32 v146, 0, v146
	v_add_f32_e32 v147, 1.0, v147
	v_cmp_gt_f32_e32 vcc, s80, v147
	s_nop 1
	v_cndmask_b32_e64 v183, 0, 32, vcc
	v_ldexp_f32 v147, v147, v183
	v_log_f32_e32 v147, v147
	v_cndmask_b32_e32 v183, 0, v214, vcc
	v_mul_f32_e32 v184, 0x3f317217, v147
	v_fma_f32 v184, v147, s85, -v184
	v_fmac_f32_e32 v184, 0x3377d1cf, v147
	v_fmac_f32_e32 v184, 0x3f317217, v147
	v_cmp_lt_f32_e64 vcc, |v147|, s55
	s_nop 1
	v_cndmask_b32_e32 v147, v147, v184, vcc
	v_sub_f32_e32 v147, v147, v183
	v_sub_f32_e32 v146, v146, v147
	global_store_dword v[148:149], v146, off offset:192
	flat_load_dword v146, v[140:141] offset:8
	s_waitcnt vmcnt(0) lgkmcnt(0)
	v_add_f32_e32 v146, v88, v146
	v_mul_f32_e64 v147, |v146|, s18
	v_exp_f32_e32 v147, v147
	v_min_f32_e32 v146, 0, v146
	v_add_f32_e32 v147, 1.0, v147
	v_cmp_gt_f32_e32 vcc, s80, v147
	s_nop 1
	v_cndmask_b32_e64 v148, 0, 32, vcc
	v_ldexp_f32 v147, v147, v148
	v_log_f32_e32 v147, v147
	v_cndmask_b32_e32 v148, 0, v214, vcc
	v_mul_f32_e32 v149, 0x3f317217, v147
	v_fma_f32 v149, v147, s85, -v149
	v_fmac_f32_e32 v149, 0x3377d1cf, v147
	v_fmac_f32_e32 v149, 0x3f317217, v147
	v_cmp_lt_f32_e64 vcc, |v147|, s55
	s_nop 1
	v_cndmask_b32_e32 v147, v147, v149, vcc
	v_sub_f32_e32 v147, v147, v148
	v_sub_f32_e32 v146, v146, v147
	global_store_dword v[150:151], v146, off offset:192
	flat_load_dword v146, v[140:141] offset:12
	s_waitcnt vmcnt(0) lgkmcnt(0)
	v_add_f32_e32 v146, v89, v146
	v_mul_f32_e64 v147, |v146|, s18
	v_exp_f32_e32 v147, v147
	v_min_f32_e32 v146, 0, v146
	v_add_f32_e32 v147, 1.0, v147
	v_cmp_gt_f32_e32 vcc, s80, v147
	s_nop 1
	v_cndmask_b32_e64 v148, 0, 32, vcc
	v_ldexp_f32 v147, v147, v148
	v_log_f32_e32 v147, v147
	v_cndmask_b32_e32 v148, 0, v214, vcc
	v_mul_f32_e32 v149, 0x3f317217, v147
	v_fma_f32 v149, v147, s85, -v149
	v_fmac_f32_e32 v149, 0x3377d1cf, v147
	v_fmac_f32_e32 v149, 0x3f317217, v147
	v_cmp_lt_f32_e64 vcc, |v147|, s55
	s_nop 1
	v_cndmask_b32_e32 v147, v147, v149, vcc
	v_sub_f32_e32 v147, v147, v148
	v_sub_f32_e32 v146, v146, v147
	global_store_dword v[152:153], v146, off offset:192
	flat_load_dword v146, v[140:141] offset:16
	s_waitcnt vmcnt(0) lgkmcnt(0)
	v_add_f32_e32 v146, v78, v146
	v_mul_f32_e64 v147, |v146|, s18
	v_exp_f32_e32 v147, v147
	v_min_f32_e32 v146, 0, v146
	v_add_f32_e32 v147, 1.0, v147
	v_cmp_gt_f32_e32 vcc, s80, v147
	s_nop 1
	v_cndmask_b32_e64 v148, 0, 32, vcc
	v_ldexp_f32 v147, v147, v148
	v_log_f32_e32 v147, v147
	v_cndmask_b32_e32 v148, 0, v214, vcc
	v_mul_f32_e32 v149, 0x3f317217, v147
	v_fma_f32 v149, v147, s85, -v149
	v_fmac_f32_e32 v149, 0x3377d1cf, v147
	v_fmac_f32_e32 v149, 0x3f317217, v147
	v_cmp_lt_f32_e64 vcc, |v147|, s55
	s_nop 1
	v_cndmask_b32_e32 v147, v147, v149, vcc
	v_sub_f32_e32 v147, v147, v148
	v_sub_f32_e32 v146, v146, v147
	global_store_dword v[154:155], v146, off offset:192
	flat_load_dword v146, v[140:141] offset:20
	s_waitcnt vmcnt(0) lgkmcnt(0)
; template <int MODE> __device__ __forceinline__ void gemm_epilogue(f32x4 (&acc)[2][2][4][2], const GD& g, const pg8::Unit& u, int wr, int wc, int fr, int fq, LAS unsigned char* lds, const float (&rsv)[2][4]) {
;     ...
;         } else if (wc == 0 && fq < 2) {
;             float* FL = (float*)g.o3; const float* bfv = g.f0;
; #pragma unroll
;             for (int ai = 0; ai < 2; ++ai)
; #pragma unroll
;                 for (int m = 0; m < 4; ++m) { const int row = rt + ai * 128 + m * 16;
; #pragma unroll
;                     for (int n = 0; n < 2; ++n) { f32x4 v = acc[ai][0][m][n];
; #pragma unroll
;                         for (int j = 0; j < 4; ++j) { const int hh = 8 * fq + 4 * n + j; const float x = v[j] + bfv[hh];
;                             FL[(size_t)((row >> 12) * 16 + hh) * 4096 + (row & 4095)] = fminf(x, 0.f) - __logf(1.f + __expf(-fabsf(x))); } } }
	v_add_f32_e32 v146, v79, v146
	v_mul_f32_e64 v147, |v146|, s18
	v_exp_f32_e32 v147, v147
	v_min_f32_e32 v146, 0, v146
	v_add_f32_e32 v147, 1.0, v147
	v_cmp_gt_f32_e32 vcc, s80, v147
	s_nop 1
	v_cndmask_b32_e64 v148, 0, 32, vcc
	v_ldexp_f32 v147, v147, v148
	v_log_f32_e32 v147, v147
	v_cndmask_b32_e32 v148, 0, v214, vcc
	v_mul_f32_e32 v149, 0x3f317217, v147
	v_fma_f32 v149, v147, s85, -v149
	v_fmac_f32_e32 v149, 0x3377d1cf, v147
	v_fmac_f32_e32 v149, 0x3f317217, v147
	v_cmp_lt_f32_e64 vcc, |v147|, s55
	s_nop 1
	v_cndmask_b32_e32 v147, v147, v149, vcc
	v_sub_f32_e32 v147, v147, v148
	v_sub_f32_e32 v146, v146, v147
	global_store_dword v[156:157], v146, off offset:192
	flat_load_dword v146, v[140:141] offset:24
	s_waitcnt vmcnt(0) lgkmcnt(0)
	v_add_f32_e32 v146, v80, v146
	v_mul_f32_e64 v147, |v146|, s18
	v_exp_f32_e32 v147, v147
	v_min_f32_e32 v146, 0, v146
	v_add_f32_e32 v147, 1.0, v147
	v_cmp_gt_f32_e32 vcc, s80, v147
	s_nop 1
	v_cndmask_b32_e64 v148, 0, 32, vcc
	v_ldexp_f32 v147, v147, v148
	v_log_f32_e32 v147, v147
	v_cndmask_b32_e32 v148, 0, v214, vcc
	v_mul_f32_e32 v149, 0x3f317217, v147
	v_fma_f32 v149, v147, s85, -v149
	v_fmac_f32_e32 v149, 0x3377d1cf, v147
	v_fmac_f32_e32 v149, 0x3f317217, v147
	v_cmp_lt_f32_e64 vcc, |v147|, s55
	s_nop 1
	v_cndmask_b32_e32 v147, v147, v149, vcc
	v_sub_f32_e32 v147, v147, v148
	v_sub_f32_e32 v146, v146, v147
	global_store_dword v[158:159], v146, off offset:192
	flat_load_dword v146, v[140:141] offset:28
	s_waitcnt vmcnt(0) lgkmcnt(0)
	v_add_f32_e32 v146, v81, v146
	v_mul_f32_e64 v147, |v146|, s18
	v_exp_f32_e32 v147, v147
	v_min_f32_e32 v146, 0, v146
	v_add_f32_e32 v147, 1.0, v147
	v_cmp_gt_f32_e32 vcc, s80, v147
	s_nop 1
	v_cndmask_b32_e64 v148, 0, 32, vcc
	v_ldexp_f32 v147, v147, v148
	v_log_f32_e32 v147, v147
	v_cndmask_b32_e32 v148, 0, v214, vcc
	v_mul_f32_e32 v149, 0x3f317217, v147
	v_fma_f32 v149, v147, s85, -v149
	v_fmac_f32_e32 v149, 0x3377d1cf, v147
	v_fmac_f32_e32 v149, 0x3f317217, v147
	v_cmp_lt_f32_e64 vcc, |v147|, s55
	s_nop 1
	v_cndmask_b32_e32 v147, v147, v149, vcc
	v_sub_f32_e32 v147, v147, v148
	v_sub_f32_e32 v146, v146, v147
	global_store_dword v[160:161], v146, off offset:192
	flat_load_dword v148, v[140:141]
	v_add_u32_e32 v146, 0x80, v1
	v_ashrrev_i32_e32 v149, 8, v146
	v_and_b32_e32 v146, 0xfcf, v146
	v_mov_b32_e32 v147, v0
	v_lshlrev_b32_e32 v146, 2, v146
	v_lshl_add_u64 v[160:161], s[2:3], 0, v[146:147]
	v_and_b32_e32 v183, -16, v149
	s_waitcnt vmcnt(0) lgkmcnt(0)
	v_add_f32_e32 v148, v62, v148
	v_mul_f32_e64 v146, |v148|, s18
	v_exp_f32_e32 v149, v146
	v_or_b32_e32 v146, v183, v172
	v_ashrrev_i32_e32 v147, 31, v146
	v_lshlrev_b64 v[146:147], 14, v[146:147]
	v_add_f32_e32 v149, 1.0, v149
	v_cmp_gt_f32_e32 vcc, s80, v149
	v_min_f32_e32 v148, 0, v148
	v_lshl_add_u64 v[146:147], v[160:161], 0, v[146:147]
	v_cndmask_b32_e64 v150, 0, 32, vcc
	v_ldexp_f32 v149, v149, v150
	v_log_f32_e32 v149, v149
	v_cndmask_b32_e32 v150, 0, v214, vcc
	v_mul_f32_e32 v151, 0x3f317217, v149
	v_fma_f32 v151, v149, s85, -v151
	v_fmac_f32_e32 v151, 0x3377d1cf, v149
	v_fmac_f32_e32 v151, 0x3f317217, v149
	v_cmp_lt_f32_e64 vcc, |v149|, s55
	s_nop 1
	v_cndmask_b32_e32 v149, v149, v151, vcc
	v_sub_f32_e32 v149, v149, v150
	v_sub_f32_e32 v148, v148, v149
	global_store_dword v[146:147], v148, off
	flat_load_dword v148, v[140:141] offset:4
	s_waitcnt vmcnt(0) lgkmcnt(0)
	v_add_f32_e32 v150, v63, v148
	v_mul_f32_e64 v148, |v150|, s18
	v_exp_f32_e32 v151, v148
	v_or_b32_e32 v148, v183, v174
	v_ashrrev_i32_e32 v149, 31, v148
	v_lshlrev_b64 v[148:149], 14, v[148:149]
	v_add_f32_e32 v151, 1.0, v151
	v_cmp_gt_f32_e32 vcc, s80, v151
	v_min_f32_e32 v150, 0, v150
	v_lshl_add_u64 v[148:149], v[160:161], 0, v[148:149]
	v_cndmask_b32_e64 v152, 0, 32, vcc
	v_ldexp_f32 v151, v151, v152
	v_log_f32_e32 v151, v151
	v_cndmask_b32_e32 v152, 0, v214, vcc
	v_mul_f32_e32 v153, 0x3f317217, v151
	v_fma_f32 v153, v151, s85, -v153
	v_fmac_f32_e32 v153, 0x3377d1cf, v151
	v_fmac_f32_e32 v153, 0x3f317217, v151
	v_cmp_lt_f32_e64 vcc, |v151|, s55
	s_nop 1
	v_cndmask_b32_e32 v151, v151, v153, vcc
	v_sub_f32_e32 v151, v151, v152
	v_sub_f32_e32 v150, v150, v151
	global_store_dword v[148:149], v150, off
	flat_load_dword v150, v[140:141] offset:8
	s_waitcnt vmcnt(0) lgkmcnt(0)
	v_add_f32_e32 v152, v64, v150
	v_mul_f32_e64 v150, |v152|, s18
	v_exp_f32_e32 v153, v150
	v_or_b32_e32 v150, v183, v175
	v_ashrrev_i32_e32 v151, 31, v150
	v_lshlrev_b64 v[150:151], 14, v[150:151]
	v_add_f32_e32 v153, 1.0, v153
	v_cmp_gt_f32_e32 vcc, s80, v153
	v_min_f32_e32 v152, 0, v152
	v_lshl_add_u64 v[150:151], v[160:161], 0, v[150:151]
	v_cndmask_b32_e64 v154, 0, 32, vcc
	v_ldexp_f32 v153, v153, v154
	v_log_f32_e32 v153, v153
	v_cndmask_b32_e32 v154, 0, v214, vcc
	v_mul_f32_e32 v155, 0x3f317217, v153
	v_fma_f32 v155, v153, s85, -v155
	v_fmac_f32_e32 v155, 0x3377d1cf, v153
	v_fmac_f32_e32 v155, 0x3f317217, v153
	v_cmp_lt_f32_e64 vcc, |v153|, s55
	s_nop 1
	v_cndmask_b32_e32 v153, v153, v155, vcc
	v_sub_f32_e32 v153, v153, v154
	v_sub_f32_e32 v152, v152, v153
	global_store_dword v[150:151], v152, off
	flat_load_dword v152, v[140:141] offset:12
	s_waitcnt vmcnt(0) lgkmcnt(0)
	v_add_f32_e32 v154, v65, v152
	v_mul_f32_e64 v152, |v154|, s18
	v_exp_f32_e32 v155, v152
	v_or_b32_e32 v152, v183, v176
	v_ashrrev_i32_e32 v153, 31, v152
	v_lshlrev_b64 v[152:153], 14, v[152:153]
	v_add_f32_e32 v155, 1.0, v155
	v_cmp_gt_f32_e32 vcc, s80, v155
	v_min_f32_e32 v154, 0, v154
	v_lshl_add_u64 v[152:153], v[160:161], 0, v[152:153]
	v_cndmask_b32_e64 v156, 0, 32, vcc
	v_ldexp_f32 v155, v155, v156
	v_log_f32_e32 v155, v155
	v_cndmask_b32_e32 v156, 0, v214, vcc
	v_mul_f32_e32 v157, 0x3f317217, v155
	v_fma_f32 v157, v155, s85, -v157
	v_fmac_f32_e32 v157, 0x3377d1cf, v155
	v_fmac_f32_e32 v157, 0x3f317217, v155
	v_cmp_lt_f32_e64 vcc, |v155|, s55
	s_nop 1
	v_cndmask_b32_e32 v155, v155, v157, vcc
	v_sub_f32_e32 v155, v155, v156
	v_sub_f32_e32 v154, v154, v155
	global_store_dword v[152:153], v154, off
	flat_load_dword v154, v[140:141] offset:16
	s_waitcnt vmcnt(0) lgkmcnt(0)
; template <int MODE> __device__ __forceinline__ void gemm_epilogue(f32x4 (&acc)[2][2][4][2], const GD& g, const pg8::Unit& u, int wr, int wc, int fr, int fq, LAS unsigned char* lds, const float (&rsv)[2][4]) {
;     ...
;         } else if (wc == 0 && fq < 2) {
;             float* FL = (float*)g.o3; const float* bfv = g.f0;
; #pragma unroll
;             for (int ai = 0; ai < 2; ++ai)
; #pragma unroll
;                 for (int m = 0; m < 4; ++m) { const int row = rt + ai * 128 + m * 16;
; #pragma unroll
;                     for (int n = 0; n < 2; ++n) { f32x4 v = acc[ai][0][m][n];
; #pragma unroll
;                         for (int j = 0; j < 4; ++j) { const int hh = 8 * fq + 4 * n + j; const float x = v[j] + bfv[hh];
;                             FL[(size_t)((row >> 12) * 16 + hh) * 4096 + (row & 4095)] = fminf(x, 0.f) - __logf(1.f + __expf(-fabsf(x))); } } }
	v_add_f32_e32 v156, v58, v154
	v_mul_f32_e64 v154, |v156|, s18
	v_exp_f32_e32 v157, v154
	v_or_b32_e32 v154, v183, v177
	v_ashrrev_i32_e32 v155, 31, v154
	v_lshlrev_b64 v[154:155], 14, v[154:155]
	v_add_f32_e32 v157, 1.0, v157
	v_cmp_gt_f32_e32 vcc, s80, v157
	v_min_f32_e32 v156, 0, v156
	v_lshl_add_u64 v[154:155], v[160:161], 0, v[154:155]
	v_cndmask_b32_e64 v158, 0, 32, vcc
	v_ldexp_f32 v157, v157, v158
	v_log_f32_e32 v157, v157
	v_cndmask_b32_e32 v158, 0, v214, vcc
	v_mul_f32_e32 v159, 0x3f317217, v157
	v_fma_f32 v159, v157, s85, -v159
	v_fmac_f32_e32 v159, 0x3377d1cf, v157
	v_fmac_f32_e32 v159, 0x3f317217, v157
	v_cmp_lt_f32_e64 vcc, |v157|, s55
	s_nop 1
	v_cndmask_b32_e32 v157, v157, v159, vcc
	v_sub_f32_e32 v157, v157, v158
	v_sub_f32_e32 v156, v156, v157
	global_store_dword v[154:155], v156, off
	flat_load_dword v156, v[140:141] offset:20
	s_waitcnt vmcnt(0) lgkmcnt(0)
	v_add_f32_e32 v158, v59, v156
	v_mul_f32_e64 v156, |v158|, s18
	v_exp_f32_e32 v159, v156
	v_or_b32_e32 v156, v183, v178
	v_ashrrev_i32_e32 v157, 31, v156
	v_lshlrev_b64 v[156:157], 14, v[156:157]
	v_add_f32_e32 v159, 1.0, v159
	v_cmp_gt_f32_e32 vcc, s80, v159
	v_min_f32_e32 v158, 0, v158
	v_lshl_add_u64 v[156:157], v[160:161], 0, v[156:157]
	v_cndmask_b32_e64 v184, 0, 32, vcc
	v_ldexp_f32 v159, v159, v184
	v_log_f32_e32 v159, v159
	v_cndmask_b32_e32 v184, 0, v214, vcc
	v_mul_f32_e32 v185, 0x3f317217, v159
	v_fma_f32 v185, v159, s85, -v185
	v_fmac_f32_e32 v185, 0x3377d1cf, v159
	v_fmac_f32_e32 v185, 0x3f317217, v159
	v_cmp_lt_f32_e64 vcc, |v159|, s55
	s_nop 1
	v_cndmask_b32_e32 v159, v159, v185, vcc
	v_sub_f32_e32 v159, v159, v184
	v_sub_f32_e32 v158, v158, v159
	global_store_dword v[156:157], v158, off
	flat_load_dword v158, v[140:141] offset:24
	s_waitcnt vmcnt(0) lgkmcnt(0)
	v_add_f32_e32 v184, v60, v158
	v_mul_f32_e64 v158, |v184|, s18
	v_exp_f32_e32 v185, v158
	v_or_b32_e32 v158, v183, v179
	v_ashrrev_i32_e32 v159, 31, v158
	v_lshlrev_b64 v[158:159], 14, v[158:159]
	v_add_f32_e32 v185, 1.0, v185
	v_cmp_gt_f32_e32 vcc, s80, v185
	v_min_f32_e32 v184, 0, v184
	v_lshl_add_u64 v[158:159], v[160:161], 0, v[158:159]
	v_cndmask_b32_e64 v186, 0, 32, vcc
	v_ldexp_f32 v185, v185, v186
	v_log_f32_e32 v185, v185
	v_cndmask_b32_e32 v186, 0, v214, vcc
	v_mul_f32_e32 v187, 0x3f317217, v185
	v_fma_f32 v187, v185, s85, -v187
	v_fmac_f32_e32 v187, 0x3377d1cf, v185
	v_fmac_f32_e32 v187, 0x3f317217, v185
	v_cmp_lt_f32_e64 vcc, |v185|, s55
	s_nop 1
	v_cndmask_b32_e32 v185, v185, v187, vcc
	v_sub_f32_e32 v185, v185, v186
	v_sub_f32_e32 v184, v184, v185
	global_store_dword v[158:159], v184, off
	flat_load_dword v184, v[140:141] offset:28
	s_waitcnt vmcnt(0) lgkmcnt(0)
	v_add_f32_e32 v186, v61, v184
	v_mul_f32_e64 v184, |v186|, s18
	v_exp_f32_e32 v187, v184
	v_or_b32_e32 v184, v183, v180
	v_ashrrev_i32_e32 v185, 31, v184
	v_lshlrev_b64 v[184:185], 14, v[184:185]
	v_add_f32_e32 v183, 1.0, v187
	v_cmp_gt_f32_e32 vcc, s80, v183
	v_lshl_add_u64 v[160:161], v[160:161], 0, v[184:185]
	v_min_f32_e32 v184, 0, v186
	v_cndmask_b32_e64 v187, 0, 32, vcc
	v_ldexp_f32 v183, v183, v187
	v_log_f32_e32 v183, v183
	v_cndmask_b32_e32 v185, 0, v214, vcc
	v_mul_f32_e32 v186, 0x3f317217, v183
	v_fma_f32 v186, v183, s85, -v186
	v_fmac_f32_e32 v186, 0x3377d1cf, v183
	v_fmac_f32_e32 v186, 0x3f317217, v183
	v_cmp_lt_f32_e64 vcc, |v183|, s55
	s_nop 1
	v_cndmask_b32_e32 v183, v183, v186, vcc
	v_sub_f32_e32 v183, v183, v185
	v_sub_f32_e32 v183, v184, v183
	global_store_dword v[160:161], v183, off
	flat_load_dword v183, v[140:141]
	s_waitcnt vmcnt(0) lgkmcnt(0)
	v_add_f32_e32 v183, v54, v183
	v_mul_f32_e64 v184, |v183|, s18
	v_exp_f32_e32 v184, v184
	v_min_f32_e32 v183, 0, v183
	v_add_f32_e32 v184, 1.0, v184
	v_cmp_gt_f32_e32 vcc, s80, v184
	s_nop 1
	v_cndmask_b32_e64 v185, 0, 32, vcc
	v_ldexp_f32 v184, v184, v185
	v_log_f32_e32 v184, v184
	v_cndmask_b32_e32 v185, 0, v214, vcc
	v_mul_f32_e32 v186, 0x3f317217, v184
	v_fma_f32 v186, v184, s85, -v186
	v_fmac_f32_e32 v186, 0x3377d1cf, v184
	v_fmac_f32_e32 v186, 0x3f317217, v184
	v_cmp_lt_f32_e64 vcc, |v184|, s55
	s_nop 1
	v_cndmask_b32_e32 v184, v184, v186, vcc
	v_sub_f32_e32 v184, v184, v185
	v_sub_f32_e32 v183, v183, v184
	global_store_dword v[146:147], v183, off offset:64
	flat_load_dword v183, v[140:141] offset:4
	s_waitcnt vmcnt(0) lgkmcnt(0)
	v_add_f32_e32 v183, v55, v183
	v_mul_f32_e64 v184, |v183|, s18
	v_exp_f32_e32 v184, v184
	v_min_f32_e32 v183, 0, v183
	v_add_f32_e32 v184, 1.0, v184
	v_cmp_gt_f32_e32 vcc, s80, v184
	s_nop 1
	v_cndmask_b32_e64 v185, 0, 32, vcc
	v_ldexp_f32 v184, v184, v185
	v_log_f32_e32 v184, v184
	v_cndmask_b32_e32 v185, 0, v214, vcc
	v_mul_f32_e32 v186, 0x3f317217, v184
	v_fma_f32 v186, v184, s85, -v186
	v_fmac_f32_e32 v186, 0x3377d1cf, v184
	v_fmac_f32_e32 v186, 0x3f317217, v184
	v_cmp_lt_f32_e64 vcc, |v184|, s55
	s_nop 1
	v_cndmask_b32_e32 v184, v184, v186, vcc
	v_sub_f32_e32 v184, v184, v185
	v_sub_f32_e32 v183, v183, v184
	global_store_dword v[148:149], v183, off offset:64
	flat_load_dword v183, v[140:141] offset:8
	s_waitcnt vmcnt(0) lgkmcnt(0)
	v_add_f32_e32 v183, v56, v183
	v_mul_f32_e64 v184, |v183|, s18
	v_exp_f32_e32 v184, v184
	v_min_f32_e32 v183, 0, v183
	v_add_f32_e32 v184, 1.0, v184
	v_cmp_gt_f32_e32 vcc, s80, v184
	s_nop 1
	v_cndmask_b32_e64 v185, 0, 32, vcc
	v_ldexp_f32 v184, v184, v185
	v_log_f32_e32 v184, v184
	v_cndmask_b32_e32 v185, 0, v214, vcc
	v_mul_f32_e32 v186, 0x3f317217, v184
	v_fma_f32 v186, v184, s85, -v186
	v_fmac_f32_e32 v186, 0x3377d1cf, v184
	v_fmac_f32_e32 v186, 0x3f317217, v184
	v_cmp_lt_f32_e64 vcc, |v184|, s55
	s_nop 1
	v_cndmask_b32_e32 v184, v184, v186, vcc
	v_sub_f32_e32 v184, v184, v185
	v_sub_f32_e32 v183, v183, v184
	global_store_dword v[150:151], v183, off offset:64
	flat_load_dword v183, v[140:141] offset:12
	s_waitcnt vmcnt(0) lgkmcnt(0)
; template <int MODE> __device__ __forceinline__ void gemm_epilogue(f32x4 (&acc)[2][2][4][2], const GD& g, const pg8::Unit& u, int wr, int wc, int fr, int fq, LAS unsigned char* lds, const float (&rsv)[2][4]) {
;     ...
;         } else if (wc == 0 && fq < 2) {
;             float* FL = (float*)g.o3; const float* bfv = g.f0;
; #pragma unroll
;             for (int ai = 0; ai < 2; ++ai)
; #pragma unroll
;                 for (int m = 0; m < 4; ++m) { const int row = rt + ai * 128 + m * 16;
; #pragma unroll
;                     for (int n = 0; n < 2; ++n) { f32x4 v = acc[ai][0][m][n];
; #pragma unroll
;                         for (int j = 0; j < 4; ++j) { const int hh = 8 * fq + 4 * n + j; const float x = v[j] + bfv[hh];
;                             FL[(size_t)((row >> 12) * 16 + hh) * 4096 + (row & 4095)] = fminf(x, 0.f) - __logf(1.f + __expf(-fabsf(x))); } } }
	v_add_f32_e32 v183, v57, v183
	v_mul_f32_e64 v184, |v183|, s18
	v_exp_f32_e32 v184, v184
	v_min_f32_e32 v183, 0, v183
	v_add_f32_e32 v184, 1.0, v184
	v_cmp_gt_f32_e32 vcc, s80, v184
	s_nop 1
	v_cndmask_b32_e64 v185, 0, 32, vcc
	v_ldexp_f32 v184, v184, v185
	v_log_f32_e32 v184, v184
	v_cndmask_b32_e32 v185, 0, v214, vcc
	v_mul_f32_e32 v186, 0x3f317217, v184
	v_fma_f32 v186, v184, s85, -v186
	v_fmac_f32_e32 v186, 0x3377d1cf, v184
	v_fmac_f32_e32 v186, 0x3f317217, v184
	v_cmp_lt_f32_e64 vcc, |v184|, s55
	s_nop 1
	v_cndmask_b32_e32 v184, v184, v186, vcc
	v_sub_f32_e32 v184, v184, v185
	v_sub_f32_e32 v183, v183, v184
	global_store_dword v[152:153], v183, off offset:64
	flat_load_dword v183, v[140:141] offset:16
	s_waitcnt vmcnt(0) lgkmcnt(0)
	v_add_f32_e32 v183, v46, v183
	v_mul_f32_e64 v184, |v183|, s18
	v_exp_f32_e32 v184, v184
	v_min_f32_e32 v183, 0, v183
	v_add_f32_e32 v184, 1.0, v184
	v_cmp_gt_f32_e32 vcc, s80, v184
	s_nop 1
	v_cndmask_b32_e64 v185, 0, 32, vcc
	v_ldexp_f32 v184, v184, v185
	v_log_f32_e32 v184, v184
	v_cndmask_b32_e32 v185, 0, v214, vcc
	v_mul_f32_e32 v186, 0x3f317217, v184
	v_fma_f32 v186, v184, s85, -v186
	v_fmac_f32_e32 v186, 0x3377d1cf, v184
	v_fmac_f32_e32 v186, 0x3f317217, v184
	v_cmp_lt_f32_e64 vcc, |v184|, s55
	s_nop 1
	v_cndmask_b32_e32 v184, v184, v186, vcc
	v_sub_f32_e32 v184, v184, v185
	v_sub_f32_e32 v183, v183, v184
	global_store_dword v[154:155], v183, off offset:64
	flat_load_dword v183, v[140:141] offset:20
	s_waitcnt vmcnt(0) lgkmcnt(0)
	v_add_f32_e32 v183, v47, v183
	v_mul_f32_e64 v184, |v183|, s18
	v_exp_f32_e32 v184, v184
	v_min_f32_e32 v183, 0, v183
	v_add_f32_e32 v184, 1.0, v184
	v_cmp_gt_f32_e32 vcc, s80, v184
	s_nop 1
	v_cndmask_b32_e64 v185, 0, 32, vcc
	v_ldexp_f32 v184, v184, v185
	v_log_f32_e32 v184, v184
	v_cndmask_b32_e32 v185, 0, v214, vcc
	v_mul_f32_e32 v186, 0x3f317217, v184
	v_fma_f32 v186, v184, s85, -v186
	v_fmac_f32_e32 v186, 0x3377d1cf, v184
	v_fmac_f32_e32 v186, 0x3f317217, v184
	v_cmp_lt_f32_e64 vcc, |v184|, s55
	s_nop 1
	v_cndmask_b32_e32 v184, v184, v186, vcc
	v_sub_f32_e32 v184, v184, v185
	v_sub_f32_e32 v183, v183, v184
	global_store_dword v[156:157], v183, off offset:64
	flat_load_dword v183, v[140:141] offset:24
	s_waitcnt vmcnt(0) lgkmcnt(0)
	v_add_f32_e32 v183, v48, v183
	v_mul_f32_e64 v184, |v183|, s18
	v_exp_f32_e32 v184, v184
	v_min_f32_e32 v183, 0, v183
	v_add_f32_e32 v184, 1.0, v184
	v_cmp_gt_f32_e32 vcc, s80, v184
	s_nop 1
	v_cndmask_b32_e64 v185, 0, 32, vcc
	v_ldexp_f32 v184, v184, v185
	v_log_f32_e32 v184, v184
	v_cndmask_b32_e32 v185, 0, v214, vcc
	v_mul_f32_e32 v186, 0x3f317217, v184
	v_fma_f32 v186, v184, s85, -v186
	v_fmac_f32_e32 v186, 0x3377d1cf, v184
	v_fmac_f32_e32 v186, 0x3f317217, v184
	v_cmp_lt_f32_e64 vcc, |v184|, s55
	s_nop 1
	v_cndmask_b32_e32 v184, v184, v186, vcc
	v_sub_f32_e32 v184, v184, v185
	v_sub_f32_e32 v183, v183, v184
	global_store_dword v[158:159], v183, off offset:64
	flat_load_dword v183, v[140:141] offset:28
	s_waitcnt vmcnt(0) lgkmcnt(0)
	v_add_f32_e32 v183, v49, v183
	v_mul_f32_e64 v184, |v183|, s18
	v_exp_f32_e32 v184, v184
	v_min_f32_e32 v183, 0, v183
	v_add_f32_e32 v184, 1.0, v184
	v_cmp_gt_f32_e32 vcc, s80, v184
	s_nop 1
	v_cndmask_b32_e64 v185, 0, 32, vcc
	v_ldexp_f32 v184, v184, v185
	v_log_f32_e32 v184, v184
	v_cndmask_b32_e32 v185, 0, v214, vcc
	v_mul_f32_e32 v186, 0x3f317217, v184
	v_fma_f32 v186, v184, s85, -v186
	v_fmac_f32_e32 v186, 0x3377d1cf, v184
	v_fmac_f32_e32 v186, 0x3f317217, v184
	v_cmp_lt_f32_e64 vcc, |v184|, s55
	s_nop 1
	v_cndmask_b32_e32 v184, v184, v186, vcc
	v_sub_f32_e32 v184, v184, v185
	v_sub_f32_e32 v183, v183, v184
	global_store_dword v[160:161], v183, off offset:64
	flat_load_dword v183, v[140:141]
	s_waitcnt vmcnt(0) lgkmcnt(0)
	v_add_f32_e32 v183, v38, v183
	v_mul_f32_e64 v184, |v183|, s18
	v_exp_f32_e32 v184, v184
	v_min_f32_e32 v183, 0, v183
	v_add_f32_e32 v184, 1.0, v184
	v_cmp_gt_f32_e32 vcc, s80, v184
	s_nop 1
	v_cndmask_b32_e64 v185, 0, 32, vcc
	v_ldexp_f32 v184, v184, v185
	v_log_f32_e32 v184, v184
	v_cndmask_b32_e32 v185, 0, v214, vcc
	v_mul_f32_e32 v186, 0x3f317217, v184
	v_fma_f32 v186, v184, s85, -v186
	v_fmac_f32_e32 v186, 0x3377d1cf, v184
	v_fmac_f32_e32 v186, 0x3f317217, v184
	v_cmp_lt_f32_e64 vcc, |v184|, s55
	s_nop 1
	v_cndmask_b32_e32 v184, v184, v186, vcc
	v_sub_f32_e32 v184, v184, v185
	v_sub_f32_e32 v183, v183, v184
	global_store_dword v[146:147], v183, off offset:128
	flat_load_dword v183, v[140:141] offset:4
	s_waitcnt vmcnt(0) lgkmcnt(0)
	v_add_f32_e32 v183, v39, v183
	v_mul_f32_e64 v184, |v183|, s18
	v_exp_f32_e32 v184, v184
	v_min_f32_e32 v183, 0, v183
	v_add_f32_e32 v184, 1.0, v184
	v_cmp_gt_f32_e32 vcc, s80, v184
	s_nop 1
	v_cndmask_b32_e64 v185, 0, 32, vcc
	v_ldexp_f32 v184, v184, v185
	v_log_f32_e32 v184, v184
	v_cndmask_b32_e32 v185, 0, v214, vcc
	v_mul_f32_e32 v186, 0x3f317217, v184
	v_fma_f32 v186, v184, s85, -v186
	v_fmac_f32_e32 v186, 0x3377d1cf, v184
	v_fmac_f32_e32 v186, 0x3f317217, v184
	v_cmp_lt_f32_e64 vcc, |v184|, s55
	s_nop 1
	v_cndmask_b32_e32 v184, v184, v186, vcc
	v_sub_f32_e32 v184, v184, v185
	v_sub_f32_e32 v183, v183, v184
	global_store_dword v[148:149], v183, off offset:128
	flat_load_dword v183, v[140:141] offset:8
	s_waitcnt vmcnt(0) lgkmcnt(0)
	v_add_f32_e32 v183, v40, v183
	v_mul_f32_e64 v184, |v183|, s18
	v_exp_f32_e32 v184, v184
	v_min_f32_e32 v183, 0, v183
	v_add_f32_e32 v184, 1.0, v184
	v_cmp_gt_f32_e32 vcc, s80, v184
	s_nop 1
	v_cndmask_b32_e64 v185, 0, 32, vcc
	v_ldexp_f32 v184, v184, v185
	v_log_f32_e32 v184, v184
	v_cndmask_b32_e32 v185, 0, v214, vcc
	v_mul_f32_e32 v186, 0x3f317217, v184
	v_fma_f32 v186, v184, s85, -v186
	v_fmac_f32_e32 v186, 0x3377d1cf, v184
	v_fmac_f32_e32 v186, 0x3f317217, v184
	v_cmp_lt_f32_e64 vcc, |v184|, s55
	s_nop 1
	v_cndmask_b32_e32 v184, v184, v186, vcc
	v_sub_f32_e32 v184, v184, v185
	v_sub_f32_e32 v183, v183, v184
	global_store_dword v[150:151], v183, off offset:128
	flat_load_dword v183, v[140:141] offset:12
	s_waitcnt vmcnt(0) lgkmcnt(0)
; template <int MODE> __device__ __forceinline__ void gemm_epilogue(f32x4 (&acc)[2][2][4][2], const GD& g, const pg8::Unit& u, int wr, int wc, int fr, int fq, LAS unsigned char* lds, const float (&rsv)[2][4]) {
;     ...
;         } else if (wc == 0 && fq < 2) {
;             float* FL = (float*)g.o3; const float* bfv = g.f0;
; #pragma unroll
;             for (int ai = 0; ai < 2; ++ai)
; #pragma unroll
;                 for (int m = 0; m < 4; ++m) { const int row = rt + ai * 128 + m * 16;
; #pragma unroll
;                     for (int n = 0; n < 2; ++n) { f32x4 v = acc[ai][0][m][n];
; #pragma unroll
;                         for (int j = 0; j < 4; ++j) { const int hh = 8 * fq + 4 * n + j; const float x = v[j] + bfv[hh];
;                             FL[(size_t)((row >> 12) * 16 + hh) * 4096 + (row & 4095)] = fminf(x, 0.f) - __logf(1.f + __expf(-fabsf(x))); } } }
	v_add_f32_e32 v183, v41, v183
	v_mul_f32_e64 v184, |v183|, s18
	v_exp_f32_e32 v184, v184
	v_min_f32_e32 v183, 0, v183
	v_add_f32_e32 v184, 1.0, v184
	v_cmp_gt_f32_e32 vcc, s80, v184
	s_nop 1
	v_cndmask_b32_e64 v185, 0, 32, vcc
	v_ldexp_f32 v184, v184, v185
	v_log_f32_e32 v184, v184
	v_cndmask_b32_e32 v185, 0, v214, vcc
	v_mul_f32_e32 v186, 0x3f317217, v184
	v_fma_f32 v186, v184, s85, -v186
	v_fmac_f32_e32 v186, 0x3377d1cf, v184
	v_fmac_f32_e32 v186, 0x3f317217, v184
	v_cmp_lt_f32_e64 vcc, |v184|, s55
	s_nop 1
	v_cndmask_b32_e32 v184, v184, v186, vcc
	v_sub_f32_e32 v184, v184, v185
	v_sub_f32_e32 v183, v183, v184
	global_store_dword v[152:153], v183, off offset:128
	flat_load_dword v183, v[140:141] offset:16
	s_waitcnt vmcnt(0) lgkmcnt(0)
	v_add_f32_e32 v183, v30, v183
	v_mul_f32_e64 v184, |v183|, s18
	v_exp_f32_e32 v184, v184
	v_min_f32_e32 v183, 0, v183
	v_add_f32_e32 v184, 1.0, v184
	v_cmp_gt_f32_e32 vcc, s80, v184
	s_nop 1
	v_cndmask_b32_e64 v185, 0, 32, vcc
	v_ldexp_f32 v184, v184, v185
	v_log_f32_e32 v184, v184
	v_cndmask_b32_e32 v185, 0, v214, vcc
	v_mul_f32_e32 v186, 0x3f317217, v184
	v_fma_f32 v186, v184, s85, -v186
	v_fmac_f32_e32 v186, 0x3377d1cf, v184
	v_fmac_f32_e32 v186, 0x3f317217, v184
	v_cmp_lt_f32_e64 vcc, |v184|, s55
	s_nop 1
	v_cndmask_b32_e32 v184, v184, v186, vcc
	v_sub_f32_e32 v184, v184, v185
	v_sub_f32_e32 v183, v183, v184
	global_store_dword v[154:155], v183, off offset:128
	flat_load_dword v183, v[140:141] offset:20
	s_waitcnt vmcnt(0) lgkmcnt(0)
	v_add_f32_e32 v183, v31, v183
	v_mul_f32_e64 v184, |v183|, s18
	v_exp_f32_e32 v184, v184
	v_min_f32_e32 v183, 0, v183
	v_add_f32_e32 v184, 1.0, v184
	v_cmp_gt_f32_e32 vcc, s80, v184
	s_nop 1
	v_cndmask_b32_e64 v185, 0, 32, vcc
	v_ldexp_f32 v184, v184, v185
	v_log_f32_e32 v184, v184
	v_cndmask_b32_e32 v185, 0, v214, vcc
	v_mul_f32_e32 v186, 0x3f317217, v184
	v_fma_f32 v186, v184, s85, -v186
	v_fmac_f32_e32 v186, 0x3377d1cf, v184
	v_fmac_f32_e32 v186, 0x3f317217, v184
	v_cmp_lt_f32_e64 vcc, |v184|, s55
	s_nop 1
	v_cndmask_b32_e32 v184, v184, v186, vcc
	v_sub_f32_e32 v184, v184, v185
	v_sub_f32_e32 v183, v183, v184
	global_store_dword v[156:157], v183, off offset:128
	flat_load_dword v183, v[140:141] offset:24
	s_waitcnt vmcnt(0) lgkmcnt(0)
	v_add_f32_e32 v183, v32, v183
	v_mul_f32_e64 v184, |v183|, s18
	v_exp_f32_e32 v184, v184
	v_min_f32_e32 v183, 0, v183
	v_add_f32_e32 v184, 1.0, v184
	v_cmp_gt_f32_e32 vcc, s80, v184
	s_nop 1
	v_cndmask_b32_e64 v185, 0, 32, vcc
	v_ldexp_f32 v184, v184, v185
	v_log_f32_e32 v184, v184
	v_cndmask_b32_e32 v185, 0, v214, vcc
	v_mul_f32_e32 v186, 0x3f317217, v184
	v_fma_f32 v186, v184, s85, -v186
	v_fmac_f32_e32 v186, 0x3377d1cf, v184
	v_fmac_f32_e32 v186, 0x3f317217, v184
	v_cmp_lt_f32_e64 vcc, |v184|, s55
	s_nop 1
	v_cndmask_b32_e32 v184, v184, v186, vcc
	v_sub_f32_e32 v184, v184, v185
	v_sub_f32_e32 v183, v183, v184
	global_store_dword v[158:159], v183, off offset:128
	flat_load_dword v183, v[140:141] offset:28
	s_waitcnt vmcnt(0) lgkmcnt(0)
	v_add_f32_e32 v183, v33, v183
	v_mul_f32_e64 v184, |v183|, s18
	v_exp_f32_e32 v184, v184
	v_min_f32_e32 v183, 0, v183
	v_add_f32_e32 v184, 1.0, v184
	v_cmp_gt_f32_e32 vcc, s80, v184
	s_nop 1
	v_cndmask_b32_e64 v185, 0, 32, vcc
	v_ldexp_f32 v184, v184, v185
	v_log_f32_e32 v184, v184
	v_cndmask_b32_e32 v185, 0, v214, vcc
	v_mul_f32_e32 v186, 0x3f317217, v184
	v_fma_f32 v186, v184, s85, -v186
	v_fmac_f32_e32 v186, 0x3377d1cf, v184
	v_fmac_f32_e32 v186, 0x3f317217, v184
	v_cmp_lt_f32_e64 vcc, |v184|, s55
	s_nop 1
	v_cndmask_b32_e32 v184, v184, v186, vcc
	v_sub_f32_e32 v184, v184, v185
	v_sub_f32_e32 v183, v183, v184
	global_store_dword v[160:161], v183, off offset:128
	flat_load_dword v183, v[140:141]
	s_waitcnt vmcnt(0) lgkmcnt(0)
	v_add_f32_e32 v183, v22, v183
	v_mul_f32_e64 v184, |v183|, s18
	v_exp_f32_e32 v184, v184
	v_min_f32_e32 v183, 0, v183
	v_add_f32_e32 v184, 1.0, v184
	v_cmp_gt_f32_e32 vcc, s80, v184
	s_nop 1
	v_cndmask_b32_e64 v185, 0, 32, vcc
	v_ldexp_f32 v184, v184, v185
	v_log_f32_e32 v184, v184
	v_cndmask_b32_e32 v185, 0, v214, vcc
	v_mul_f32_e32 v186, 0x3f317217, v184
	v_fma_f32 v186, v184, s85, -v186
	v_fmac_f32_e32 v186, 0x3377d1cf, v184
	v_fmac_f32_e32 v186, 0x3f317217, v184
	v_cmp_lt_f32_e64 vcc, |v184|, s55
	s_nop 1
	v_cndmask_b32_e32 v184, v184, v186, vcc
	v_sub_f32_e32 v184, v184, v185
	v_sub_f32_e32 v183, v183, v184
	global_store_dword v[146:147], v183, off offset:192
	flat_load_dword v146, v[140:141] offset:4
	s_waitcnt vmcnt(0) lgkmcnt(0)
; template <int MODE> __device__ __forceinline__ void gemm_epilogue(f32x4 (&acc)[2][2][4][2], const GD& g, const pg8::Unit& u, int wr, int wc, int fr, int fq, LAS unsigned char* lds, const float (&rsv)[2][4]) {
;     ...
;         } else if (wc == 0 && fq < 2) {
;             float* FL = (float*)g.o3; const float* bfv = g.f0;
; #pragma unroll
;             for (int ai = 0; ai < 2; ++ai)
; #pragma unroll
;                 for (int m = 0; m < 4; ++m) { const int row = rt + ai * 128 + m * 16;
; #pragma unroll
;                     for (int n = 0; n < 2; ++n) { f32x4 v = acc[ai][0][m][n];
; #pragma unroll
;                         for (int j = 0; j < 4; ++j) { const int hh = 8 * fq + 4 * n + j; const float x = v[j] + bfv[hh];
;                             FL[(size_t)((row >> 12) * 16 + hh) * 4096 + (row & 4095)] = fminf(x, 0.f) - __logf(1.f + __expf(-fabsf(x))); } } }
	v_add_f32_e32 v146, v23, v146
	v_mul_f32_e64 v147, |v146|, s18
	v_exp_f32_e32 v147, v147
	v_min_f32_e32 v146, 0, v146
	v_add_f32_e32 v147, 1.0, v147
	v_cmp_gt_f32_e32 vcc, s80, v147
	s_nop 1
	v_cndmask_b32_e64 v183, 0, 32, vcc
	v_ldexp_f32 v147, v147, v183
	v_log_f32_e32 v147, v147
	v_cndmask_b32_e32 v183, 0, v214, vcc
	v_mul_f32_e32 v184, 0x3f317217, v147
	v_fma_f32 v184, v147, s85, -v184
	v_fmac_f32_e32 v184, 0x3377d1cf, v147
	v_fmac_f32_e32 v184, 0x3f317217, v147
	v_cmp_lt_f32_e64 vcc, |v147|, s55
	s_nop 1
	v_cndmask_b32_e32 v147, v147, v184, vcc
	v_sub_f32_e32 v147, v147, v183
	v_sub_f32_e32 v146, v146, v147
	global_store_dword v[148:149], v146, off offset:192
	flat_load_dword v146, v[140:141] offset:8
	s_waitcnt vmcnt(0) lgkmcnt(0)
	v_add_f32_e32 v146, v24, v146
	v_mul_f32_e64 v147, |v146|, s18
	v_exp_f32_e32 v147, v147
	v_min_f32_e32 v146, 0, v146
	v_add_f32_e32 v147, 1.0, v147
	v_cmp_gt_f32_e32 vcc, s80, v147
	s_nop 1
	v_cndmask_b32_e64 v148, 0, 32, vcc
	v_ldexp_f32 v147, v147, v148
	v_log_f32_e32 v147, v147
	v_cndmask_b32_e32 v148, 0, v214, vcc
	v_mul_f32_e32 v149, 0x3f317217, v147
	v_fma_f32 v149, v147, s85, -v149
	v_fmac_f32_e32 v149, 0x3377d1cf, v147
	v_fmac_f32_e32 v149, 0x3f317217, v147
	v_cmp_lt_f32_e64 vcc, |v147|, s55
	s_nop 1
	v_cndmask_b32_e32 v147, v147, v149, vcc
	v_sub_f32_e32 v147, v147, v148
	v_sub_f32_e32 v146, v146, v147
	global_store_dword v[150:151], v146, off offset:192
	flat_load_dword v146, v[140:141] offset:12
	s_waitcnt vmcnt(0) lgkmcnt(0)
	v_add_f32_e32 v146, v25, v146
	v_mul_f32_e64 v147, |v146|, s18
	v_exp_f32_e32 v147, v147
	v_min_f32_e32 v146, 0, v146
	v_add_f32_e32 v147, 1.0, v147
	v_cmp_gt_f32_e32 vcc, s80, v147
	s_nop 1
	v_cndmask_b32_e64 v148, 0, 32, vcc
	v_ldexp_f32 v147, v147, v148
	v_log_f32_e32 v147, v147
	v_cndmask_b32_e32 v148, 0, v214, vcc
	v_mul_f32_e32 v149, 0x3f317217, v147
	v_fma_f32 v149, v147, s85, -v149
	v_fmac_f32_e32 v149, 0x3377d1cf, v147
	v_fmac_f32_e32 v149, 0x3f317217, v147
	v_cmp_lt_f32_e64 vcc, |v147|, s55
	s_nop 1
	v_cndmask_b32_e32 v147, v147, v149, vcc
	v_sub_f32_e32 v147, v147, v148
	v_sub_f32_e32 v146, v146, v147
	global_store_dword v[152:153], v146, off offset:192
	flat_load_dword v146, v[140:141] offset:16
	s_waitcnt vmcnt(0) lgkmcnt(0)
	v_add_f32_e32 v146, v14, v146
	v_mul_f32_e64 v147, |v146|, s18
	v_exp_f32_e32 v147, v147
	v_min_f32_e32 v146, 0, v146
	v_add_f32_e32 v147, 1.0, v147
	v_cmp_gt_f32_e32 vcc, s80, v147
	s_nop 1
	v_cndmask_b32_e64 v148, 0, 32, vcc
	v_ldexp_f32 v147, v147, v148
	v_log_f32_e32 v147, v147
	v_cndmask_b32_e32 v148, 0, v214, vcc
	v_mul_f32_e32 v149, 0x3f317217, v147
	v_fma_f32 v149, v147, s85, -v149
	v_fmac_f32_e32 v149, 0x3377d1cf, v147
	v_fmac_f32_e32 v149, 0x3f317217, v147
	v_cmp_lt_f32_e64 vcc, |v147|, s55
	s_nop 1
	v_cndmask_b32_e32 v147, v147, v149, vcc
	v_sub_f32_e32 v147, v147, v148
	v_sub_f32_e32 v146, v146, v147
	global_store_dword v[154:155], v146, off offset:192
	flat_load_dword v146, v[140:141] offset:20
	s_waitcnt vmcnt(0) lgkmcnt(0)
	v_add_f32_e32 v146, v15, v146
	v_mul_f32_e64 v147, |v146|, s18
	v_exp_f32_e32 v147, v147
	v_min_f32_e32 v146, 0, v146
	v_add_f32_e32 v147, 1.0, v147
	v_cmp_gt_f32_e32 vcc, s80, v147
	s_nop 1
	v_cndmask_b32_e64 v148, 0, 32, vcc
	v_ldexp_f32 v147, v147, v148
	v_log_f32_e32 v147, v147
	v_cndmask_b32_e32 v148, 0, v214, vcc
	v_mul_f32_e32 v149, 0x3f317217, v147
	v_fma_f32 v149, v147, s85, -v149
	v_fmac_f32_e32 v149, 0x3377d1cf, v147
	v_fmac_f32_e32 v149, 0x3f317217, v147
	v_cmp_lt_f32_e64 vcc, |v147|, s55
	s_nop 1
	v_cndmask_b32_e32 v147, v147, v149, vcc
	v_sub_f32_e32 v147, v147, v148
	v_sub_f32_e32 v146, v146, v147
	global_store_dword v[156:157], v146, off offset:192
	flat_load_dword v146, v[140:141] offset:24
	s_waitcnt vmcnt(0) lgkmcnt(0)
	v_add_f32_e32 v146, v16, v146
	v_mul_f32_e64 v147, |v146|, s18
	v_exp_f32_e32 v147, v147
	v_min_f32_e32 v146, 0, v146
	v_add_f32_e32 v147, 1.0, v147
	v_cmp_gt_f32_e32 vcc, s80, v147
	s_nop 1
	v_cndmask_b32_e64 v148, 0, 32, vcc
	v_ldexp_f32 v147, v147, v148
	v_log_f32_e32 v147, v147
	v_cndmask_b32_e32 v148, 0, v214, vcc
	v_mul_f32_e32 v149, 0x3f317217, v147
	v_fma_f32 v149, v147, s85, -v149
	v_fmac_f32_e32 v149, 0x3377d1cf, v147
	v_fmac_f32_e32 v149, 0x3f317217, v147
	v_cmp_lt_f32_e64 vcc, |v147|, s55
	s_nop 1
	v_cndmask_b32_e32 v147, v147, v149, vcc
	v_sub_f32_e32 v147, v147, v148
	v_sub_f32_e32 v146, v146, v147
	global_store_dword v[158:159], v146, off offset:192
	flat_load_dword v146, v[140:141] offset:28
	s_waitcnt vmcnt(0) lgkmcnt(0)
	v_add_f32_e32 v146, v17, v146
	v_mul_f32_e64 v147, |v146|, s18
	v_exp_f32_e32 v147, v147
	v_min_f32_e32 v146, 0, v146
	v_add_f32_e32 v147, 1.0, v147
	v_cmp_gt_f32_e32 vcc, s80, v147
	s_nop 1
	v_cndmask_b32_e64 v148, 0, 32, vcc
	v_ldexp_f32 v147, v147, v148
	v_log_f32_e32 v147, v147
	s_nop 0
	v_mul_f32_e32 v148, 0x3f317217, v147
	v_fma_f32 v148, v147, s85, -v148
	v_fmac_f32_e32 v148, 0x3377d1cf, v147
	v_fmac_f32_e32 v148, 0x3f317217, v147
	v_cmp_lt_f32_e64 s[8:9], |v147|, s55
	s_nop 1
	v_cndmask_b32_e64 v147, v147, v148, s[8:9]
	v_cndmask_b32_e32 v148, 0, v214, vcc
	v_sub_f32_e32 v147, v147, v148
	v_sub_f32_e32 v146, v146, v147
	global_store_dword v[160:161], v146, off offset:192

; __device__ __forceinline__ unsigned cvt_pk_bf16(float lo, float hi) { f32x2 v = {lo, hi}; bf16x2_t b = __builtin_convertvector(v, bf16x2_t); return __builtin_bit_cast(unsigned, b); }
; template <int MODE> __device__ __forceinline__ void gemm_epilogue(f32x4 (&acc)[2][2][4][2], const GD& g, const pg8::Unit& u, int wr, int wc, int fr, int fq, LAS unsigned char* lds, const float (&rsv)[2][4]) {
;     ...
;         if (u.pn < 24) {
;             bf16_t* O = (bf16_t*)((char*)g.o0 + (size_t)(u.pn >> 3) * (64 * MiB));
;             const int h0 = (u.pn & 7) * 2;
; #pragma unroll
;             for (int ai = 0; ai < 2; ++ai)
; #pragma unroll
;                 for (int m = 0; m < 4; ++m) { const int row = rt + ai * 128 + m * 16, b = row >> 12, t = row & 4095;
; #pragma unroll
;                     for (int bj = 0; bj < 2; ++bj) { const f32x4 v0 = acc[ai][bj][m][0], v1 = acc[ai][bj][m][1];
;                         u32x4 w; w.x = cvt_pk_bf16(v0[0], v0[1]); w.y = cvt_pk_bf16(v0[2], v0[3]); w.z = cvt_pk_bf16(v1[0], v1[1]); w.w = cvt_pk_bf16(v1[2], v1[3]);
;                         *(u32x4*)(O + ((size_t)((b * 16 + h0 + bj) * 4096 + t)) * 128 + ct) = w; } }
.LBB0_345:
	s_lshl_b32 s1, s24, 1
	s_lshr_b32 s0, s0, 8
	s_ashr_i32 s2, s24, 3
	s_and_b32 s1, s1, 14
	s_and_b32 s0, s0, 0xffff0
	s_ashr_i32 s3, s2, 31
	s_or_b32 s0, s0, s1
	s_lshl_b64 s[2:3], s[2:3], 26
	s_lshl_b32 s0, s0, 12
	v_lshl_add_u64 v[146:147], v[138:139], 0, s[2:3]
	v_and_b32_e32 v148, 0xfcf, v1
	s_or_b32 s2, s0, 0x1000
	v_cvt_pk_bf16_f32 v114, v114, v115
	v_cvt_pk_bf16_f32 v115, v116, v117
	v_cvt_pk_bf16_f32 v116, v106, v107
	v_or_b32_e32 v106, s2, v148
	v_ashrrev_i32_e32 v107, 31, v106
	v_lshlrev_b64 v[106:107], 8, v[106:107]
	v_cvt_pk_bf16_f32 v117, v108, v109
	v_lshl_add_u64 v[106:107], v[146:147], 0, v[106:107]
	global_store_dwordx4 v[106:107], v[114:117], off
	v_cvt_pk_bf16_f32 v98, v98, v99
	v_cvt_pk_bf16_f32 v99, v100, v101
	v_or_b32_e32 v114, 16, v148
	v_cvt_pk_bf16_f32 v100, v90, v91
	v_or_b32_e32 v90, s2, v114
	v_ashrrev_i32_e32 v91, 31, v90
	v_lshlrev_b64 v[90:91], 8, v[90:91]
	v_cvt_pk_bf16_f32 v101, v92, v93
	v_lshl_add_u64 v[90:91], v[146:147], 0, v[90:91]
	global_store_dwordx4 v[90:91], v[98:101], off
	v_cvt_pk_bf16_f32 v82, v82, v83
	v_cvt_pk_bf16_f32 v83, v84, v85
	v_or_b32_e32 v98, 32, v148
	v_cvt_pk_bf16_f32 v84, v74, v75
	v_or_b32_e32 v74, s2, v98
	v_ashrrev_i32_e32 v75, 31, v74
	v_lshlrev_b64 v[74:75], 8, v[74:75]
	v_cvt_pk_bf16_f32 v85, v76, v77
	v_lshl_add_u64 v[74:75], v[146:147], 0, v[74:75]
	global_store_dwordx4 v[74:75], v[82:85], off
	v_cvt_pk_bf16_f32 v70, v70, v71
	v_cvt_pk_bf16_f32 v71, v72, v73
	v_or_b32_e32 v82, 48, v148
	v_cvt_pk_bf16_f32 v72, v66, v67
	v_or_b32_e32 v66, s2, v82
	v_ashrrev_i32_e32 v67, 31, v66
	v_lshlrev_b64 v[66:67], 8, v[66:67]
	v_cvt_pk_bf16_f32 v73, v68, v69
	v_lshl_add_u64 v[66:67], v[146:147], 0, v[66:67]
	v_add_u32_e32 v1, 0x80, v1
	global_store_dwordx4 v[66:67], v[70:73], off
	v_and_b32_e32 v66, 0xfcf, v1
	v_lshrrev_b32_e32 v1, 8, v1
	v_and_b32_e32 v1, 0xffff0, v1
	v_or_b32_e32 v1, s1, v1
	v_lshlrev_b32_e32 v1, 12, v1
	v_cvt_pk_bf16_f32 v126, v126, v127
	v_cvt_pk_bf16_f32 v127, v128, v129
	v_cvt_pk_bf16_f32 v128, v122, v123
	v_or_b32_e32 v122, s0, v148
	v_cvt_pk_bf16_f32 v62, v62, v63
	v_cvt_pk_bf16_f32 v63, v64, v65
	v_cvt_pk_bf16_f32 v64, v58, v59
	v_or_b32_e32 v58, v1, v66
	v_ashrrev_i32_e32 v123, 31, v122
	v_ashrrev_i32_e32 v59, 31, v58
	v_lshlrev_b64 v[122:123], 8, v[122:123]
	v_lshlrev_b64 v[58:59], 8, v[58:59]
	v_cvt_pk_bf16_f32 v129, v124, v125
	v_lshl_add_u64 v[122:123], v[146:147], 0, v[122:123]
	v_cvt_pk_bf16_f32 v65, v60, v61
	v_lshl_add_u64 v[58:59], v[146:147], 0, v[58:59]
	global_store_dwordx4 v[122:123], v[126:129], off
	global_store_dwordx4 v[58:59], v[62:65], off
	v_or_b32_e32 v58, 0x1000, v1
	v_cvt_pk_bf16_f32 v50, v50, v51
	v_cvt_pk_bf16_f32 v51, v52, v53
	v_cvt_pk_bf16_f32 v52, v42, v43
	v_or_b32_e32 v42, v58, v66
	v_ashrrev_i32_e32 v43, 31, v42
	v_lshlrev_b64 v[42:43], 8, v[42:43]
	v_cvt_pk_bf16_f32 v53, v44, v45
	v_lshl_add_u64 v[42:43], v[146:147], 0, v[42:43]
	global_store_dwordx4 v[42:43], v[50:53], off
	v_cvt_pk_bf16_f32 v34, v34, v35
	v_cvt_pk_bf16_f32 v35, v36, v37
	v_or_b32_e32 v50, 16, v66
	v_cvt_pk_bf16_f32 v36, v26, v27
	v_or_b32_e32 v26, v58, v50
	v_ashrrev_i32_e32 v27, 31, v26
	v_lshlrev_b64 v[26:27], 8, v[26:27]
	v_cvt_pk_bf16_f32 v37, v28, v29
	v_lshl_add_u64 v[26:27], v[146:147], 0, v[26:27]
	global_store_dwordx4 v[26:27], v[34:37], off
	v_cvt_pk_bf16_f32 v18, v18, v19
	v_cvt_pk_bf16_f32 v19, v20, v21
	v_or_b32_e32 v34, 32, v66
	v_cvt_pk_bf16_f32 v20, v10, v11
	v_or_b32_e32 v10, v58, v34
	v_ashrrev_i32_e32 v11, 31, v10
	v_lshlrev_b64 v[10:11], 8, v[10:11]
	v_cvt_pk_bf16_f32 v21, v12, v13
	v_lshl_add_u64 v[10:11], v[146:147], 0, v[10:11]
	global_store_dwordx4 v[10:11], v[18:21], off
	v_cvt_pk_bf16_f32 v108, v110, v111
	v_or_b32_e32 v110, s0, v114
	v_or_b32_e32 v18, 48, v66
	v_cvt_pk_bf16_f32 v92, v94, v95
	v_or_b32_e32 v94, s0, v98
	v_cvt_pk_bf16_f32 v76, v78, v79
	v_or_b32_e32 v78, s0, v82
	v_cvt_pk_bf16_f32 v44, v46, v47
	v_or_b32_e32 v46, v1, v50
	v_cvt_pk_bf16_f32 v28, v30, v31
	v_or_b32_e32 v30, v1, v34
	v_cvt_pk_bf16_f32 v12, v14, v15
	v_or_b32_e32 v14, v1, v18
	v_cvt_pk_bf16_f32 v6, v6, v7
	v_cvt_pk_bf16_f32 v7, v8, v9
	v_cvt_pk_bf16_f32 v8, v2, v3
	v_or_b32_e32 v2, v58, v18
	v_ashrrev_i32_e32 v111, 31, v110
	v_ashrrev_i32_e32 v95, 31, v94
	v_ashrrev_i32_e32 v79, 31, v78
	v_ashrrev_i32_e32 v47, 31, v46
	v_ashrrev_i32_e32 v31, 31, v30
	v_ashrrev_i32_e32 v15, 31, v14
	v_ashrrev_i32_e32 v3, 31, v2
	v_lshlrev_b64 v[110:111], 8, v[110:111]
	v_lshlrev_b64 v[94:95], 8, v[94:95]
	v_lshlrev_b64 v[78:79], 8, v[78:79]
	v_lshlrev_b64 v[46:47], 8, v[46:47]
	v_lshlrev_b64 v[30:31], 8, v[30:31]
	v_lshlrev_b64 v[14:15], 8, v[14:15]
	v_lshlrev_b64 v[2:3], 8, v[2:3]
	v_cvt_pk_bf16_f32 v106, v118, v119
	v_cvt_pk_bf16_f32 v107, v120, v121
	v_cvt_pk_bf16_f32 v109, v112, v113
	v_lshl_add_u64 v[110:111], v[146:147], 0, v[110:111]
	v_cvt_pk_bf16_f32 v90, v102, v103
	v_cvt_pk_bf16_f32 v91, v104, v105
	v_cvt_pk_bf16_f32 v93, v96, v97
	v_lshl_add_u64 v[94:95], v[146:147], 0, v[94:95]
	v_cvt_pk_bf16_f32 v74, v86, v87
	v_cvt_pk_bf16_f32 v75, v88, v89
	v_cvt_pk_bf16_f32 v77, v80, v81
	v_lshl_add_u64 v[78:79], v[146:147], 0, v[78:79]
	v_cvt_pk_bf16_f32 v42, v54, v55
	v_cvt_pk_bf16_f32 v43, v56, v57
	v_cvt_pk_bf16_f32 v45, v48, v49
	v_lshl_add_u64 v[46:47], v[146:147], 0, v[46:47]
	v_cvt_pk_bf16_f32 v26, v38, v39
	v_cvt_pk_bf16_f32 v27, v40, v41
	v_cvt_pk_bf16_f32 v29, v32, v33
	v_lshl_add_u64 v[30:31], v[146:147], 0, v[30:31]
	v_cvt_pk_bf16_f32 v10, v22, v23
	v_cvt_pk_bf16_f32 v11, v24, v25
	v_cvt_pk_bf16_f32 v13, v16, v17
	v_lshl_add_u64 v[14:15], v[146:147], 0, v[14:15]
	v_cvt_pk_bf16_f32 v9, v4, v5
	v_lshl_add_u64 v[2:3], v[146:147], 0, v[2:3]
	global_store_dwordx4 v[110:111], v[106:109], off
	global_store_dwordx4 v[94:95], v[90:93], off
	global_store_dwordx4 v[78:79], v[74:77], off
	global_store_dwordx4 v[46:47], v[42:45], off
	global_store_dwordx4 v[30:31], v[26:29], off
	global_store_dwordx4 v[14:15], v[10:13], off
	global_store_dwordx4 v[2:3], v[6:9], off
	s_andn2_b64 vcc, exec, s[52:53]
	s_mov_b64 s[2:3], -1
	s_cbranch_vccnz .LBB0_309
